# attention: removed per-PV s_setprio flips; one static s_setprio 1 for waves 4-7 during the attention phase (reset to 0 after)
# baseline (speedup 1.0000x reference)
; #define LAS __attribute__((address_space(3)))
; #define INPTR(k) ({ int _i = (k); asm volatile("" : "+s"(_i)); (const float*)(GAS const float*)a.in[_i]; })
; __global__ void __launch_bounds__(512, 2) mega(Args a) {
;     ...
;             } else if (sp == 4 && EN(4)) {
;                 unsigned* ctr = ctl + 64 * (1 + ck * 2 + l + 64 * rep);
;                 LAS int* s_unit = (LAS int*)(lds + LDS_CTRL);
;                 const float lam_init = (l == 0) ? 0.2f : 0.35550906f;
;                 float lam;
;                 { const float* lf = INPTR(3) + (size_t)l * 256; const float sa = wave_sum(lf[lane] * lf[64 + lane]), sb = wave_sum(lf[128 + lane] * lf[192 + lane]); lam = __expf(sa) - __expf(sb) + lam_init; lam = __uint_as_float(__builtin_amdgcn_readfirstlane(__float_as_uint(lam))); }
.LBB0_16:
	s_mul_i32 s6, s5, 0x67
	s_sext_i32_i16 s7, s6
	s_ashr_i32 s7, s7, 10
	s_bfe_u32 s6, s6, 0x1000f
	s_add_i32 s14, s7, s6
	s_bfe_i64 s[6:7], s[14:15], 0x100000
	s_add_i32 s5, s5, 9
	s_cmp_lt_u32 s5, 19
	v_writelane_b32 v253, s6, 50
	s_cselect_b64 s[22:23], -1, 0
	s_add_u32 s8, s74, 0x5000000
	v_writelane_b32 v253, s7, 51
	s_addc_u32 s9, s75, 0
	s_lshl_b64 s[6:7], s[16:17], 10
	s_lshl_b64 s[18:19], s[16:17], 11
	s_add_u32 s10, s8, s18
	s_addc_u32 s11, s9, s19
	s_mul_i32 s12, s16, 0x3600
	s_mul_hi_i32 s5, s16, 0x3600
	s_add_u32 s13, s10, s12
	s_addc_u32 s20, s11, s5
	s_mul_hi_i32 s5, s16, 0x600
	v_writelane_b32 v253, s16, 52
	s_mul_i32 s12, s16, 0x600
	s_add_u32 s12, s13, s12
	v_writelane_b32 v253, s17, 53
	v_writelane_b32 v253, s13, 54
	v_writelane_b32 v253, s20, 55
	s_addc_u32 s5, s20, s5
	v_writelane_b32 v253, s12, 56
	s_add_u32 s12, s12, s18
	v_writelane_b32 v253, s5, 57
	s_addc_u32 s5, s5, s19
	v_writelane_b32 v253, s12, 58
	s_add_u32 s12, s12, s6
	v_writelane_b32 v253, s5, 59
	s_addc_u32 s13, s5, s7
	s_add_u32 s5, s12, s18
	v_writelane_b32 v253, s18, 60
	s_addc_u32 s16, s13, s19
	v_writelane_b32 v251, s16, 0
	v_writelane_b32 v253, s19, 61
	v_writelane_b32 v253, s5, 62
	s_add_u32 s5, s5, s6
	v_writelane_b32 v253, s5, 63
	s_addc_u32 s5, s16, s7
	v_writelane_b32 v251, s5, 1
	s_mov_b64 s[18:19], -1
	s_cmp_lt_i32 s15, 4
	s_mov_b64 s[16:17], 0
	v_writelane_b32 v251, s92, 2
	v_writelane_b32 v251, s15, 3
	s_cbranch_scc1 .LBB0_1233
	s_cmp_eq_u32 s15, 4
	s_mov_b64 s[16:17], -1
	s_cbranch_scc0 .LBB0_1232
	s_sext_i32_i16 s5, s14
	s_lshl_b32 s4, s4, 1
	s_add_i32 s5, s5, s4
	s_lshl_b32 s4, s5, 6
	s_add_i32 s4, s4, 64
	s_ashr_i32 s5, s4, 31
	s_lshl_b64 s[4:5], s[4:5], 2
	v_writelane_b32 v251, s28, 4
	s_add_u32 s4, s74, s4
	s_addc_u32 s5, s75, s5
	v_writelane_b32 v251, s29, 5
	v_writelane_b32 v251, s4, 6
	v_readlane_b32 s16, v253, 50
	v_readlane_b32 s17, v253, 51
	v_writelane_b32 v251, s5, 7
	s_mov_b32 s4, 3
	s_ashr_i32 s5, s4, 31
	s_lshl_b64 s[4:5], s[4:5], 3
	s_add_u32 s4, s0, s4
	s_addc_u32 s5, s1, s5
	s_load_dwordx2 s[4:5], s[4:5], 0x0
	s_lshl_b64 s[6:7], s[16:17], 10
	v_lshlrev_b32_e32 v0, 2, v203
	v_cmp_lt_i32_e32 vcc, v185, v184
	v_writelane_b32 v251, s22, 8
	s_waitcnt lgkmcnt(0)
	s_add_u32 s4, s4, s6
	s_addc_u32 s5, s5, s7
	global_load_dword v1, v0, s[4:5]
	global_load_dword v2, v0, s[4:5] offset:256
	global_load_dword v3, v0, s[4:5] offset:512
	s_nop 0
	global_load_dword v0, v0, s[4:5] offset:768
	v_cndmask_b32_e32 v6, v183, v185, vcc
	v_lshlrev_b32_e32 v6, 2, v6
	v_cmp_lt_i32_e32 vcc, v186, v184
	s_mov_b32 s4, 4
	s_ashr_i32 s5, s4, 31
	v_cndmask_b32_e32 v7, v183, v186, vcc
	v_lshlrev_b32_e32 v7, 2, v7
	v_cmp_lt_i32_e32 vcc, v187, v184
	s_lshl_b64 s[4:5], s[4:5], 3
	s_add_u32 s4, s0, s4
	v_cndmask_b32_e32 v8, v183, v187, vcc
	v_cmp_lt_i32_e32 vcc, v188, v184
	s_addc_u32 s5, s1, s5
	s_load_dwordx2 s[4:5], s[4:5], 0x0
	v_cndmask_b32_e32 v9, v183, v188, vcc
	v_cmp_lt_i32_e32 vcc, v189, v184
	s_lshl_b64 s[6:7], s[16:17], 9
	v_cndmask_b32_e64 v4, v193, v194, s[22:23]
	s_mul_i32 s14, s92, 0x2200
	s_waitcnt lgkmcnt(0)
	s_add_u32 s42, s4, s6
	s_addc_u32 s43, s5, s7
	s_add_i32 s4, s14, 0
	v_writelane_b32 v251, s23, 9
	s_add_i32 s71, s4, 0x12800
	v_cmp_eq_u32_e64 s[62:63], 0, v202
	s_lshl_b32 s73, s92, 5
	v_sub_f32_e32 v152, 1.0, v4
	s_waitcnt vmcnt(0)
	v_mul_f32_e32 v10, v1, v2
	ds_bpermute_b32 v10, v6, v10
	s_waitcnt vmcnt(0)
	v_mul_f32_e32 v11, v3, v0
	ds_bpermute_b32 v6, v6, v11
	v_cndmask_b32_e32 v11, v183, v189, vcc
	v_cmp_lt_i32_e32 vcc, v190, v184
	s_waitcnt lgkmcnt(1)
	v_fmac_f32_e32 v10, v1, v2
	s_waitcnt lgkmcnt(0)
	v_fmac_f32_e32 v6, v3, v0
	ds_bpermute_b32 v0, v7, v10
	ds_bpermute_b32 v1, v7, v6
	v_lshlrev_b32_e32 v3, 2, v8
	v_cndmask_b32_e32 v2, v183, v190, vcc
	v_lshlrev_b32_e32 v7, 2, v9
	s_waitcnt lgkmcnt(1)
	v_add_f32_e32 v0, v10, v0
	s_waitcnt lgkmcnt(0)
	v_add_f32_e32 v1, v6, v1
	ds_bpermute_b32 v6, v3, v0
	ds_bpermute_b32 v3, v3, v1
	v_lshlrev_b32_e32 v174, 2, v2
	v_lshlrev_b32_e32 v8, 2, v11
	s_waitcnt lgkmcnt(1)
	v_add_f32_e32 v0, v0, v6
	s_waitcnt lgkmcnt(0)
	v_add_f32_e32 v1, v1, v3
	ds_bpermute_b32 v2, v7, v0
	ds_bpermute_b32 v3, v7, v1
	s_waitcnt lgkmcnt(1)
	v_add_f32_e32 v0, v0, v2
	s_waitcnt lgkmcnt(0)
	v_add_f32_e32 v1, v1, v3
	ds_bpermute_b32 v2, v8, v0
	ds_bpermute_b32 v3, v8, v1
	s_waitcnt lgkmcnt(1)
	v_add_f32_e32 v0, v0, v2
	s_waitcnt lgkmcnt(0)
	v_add_f32_e32 v1, v1, v3
	ds_bpermute_b32 v2, v174, v0
	ds_bpermute_b32 v3, v174, v1
	s_waitcnt lgkmcnt(1)
	v_add_f32_e32 v0, v0, v2
	s_waitcnt lgkmcnt(0)
	v_add_f32_e32 v1, v1, v3
	v_mul_f32_e32 v0, 0x3fb8aa3b, v0
	v_mul_f32_e32 v1, 0x3fb8aa3b, v1
	v_exp_f32_e32 v0, v0
	v_exp_f32_e32 v1, v1
	s_nop 0
	v_sub_f32_e32 v0, v0, v1
	v_add_f32_e32 v0, v4, v0
	s_nop 0
	v_readfirstlane_b32 s4, v0
	s_nop 1
	v_writelane_b32 v251, s4, 10
	v_writelane_b32 v251, s62, 11
	s_nop 1
	v_writelane_b32 v251, s63, 12
	v_writelane_b32 v251, s73, 13
	s_cmp_lt_u32 s92, 4
	s_cbranch_scc1 .Lmy_noprio
	s_setprio 1
.Lmy_noprio:
	s_branch .LBB0_140

.LBB0_163:
	v_exp_f32_e32 v49, v143
	v_exp_f32_e32 v143, v145
	v_exp_f32_e32 v4, v4
	v_exp_f32_e32 v50, v142
	v_exp_f32_e32 v142, v144
	v_add_f32_e32 v51, v143, v49
	v_exp_f32_e32 v62, v139
	v_pk_add_f32 v[52:53], v[50:51], v[4:5]
	v_exp_f32_e32 v51, v140
	v_pk_add_f32 v[52:53], v[52:53], v[52:53] op_sel_hi:[0,1]
	v_exp_f32_e32 v52, v130
	v_exp_f32_e32 v66, v131
	v_add_f32_e32 v63, v142, v51
	v_exp_f32_e32 v130, v44
	v_pk_add_f32 v[64:65], v[62:63], v[52:53]
	v_exp_f32_e32 v53, v138
	v_pk_add_f32 v[64:65], v[64:65], v[64:65] op_sel_hi:[0,1]
	v_exp_f32_e32 v63, v141
	v_exp_f32_e32 v64, v56
	v_exp_f32_e32 v138, v40
	v_exp_f32_e32 v140, v1
	v_add_f32_e32 v67, v63, v53
	v_pk_add_f32 v[68:69], v[66:67], v[64:65]
	v_exp_f32_e32 v65, v58
	v_pk_add_f32 v[68:69], v[68:69], v[68:69] op_sel_hi:[0,1]
	v_exp_f32_e32 v67, v60
	v_exp_f32_e32 v68, v54
	v_exp_f32_e32 v60, v57
	v_exp_f32_e32 v54, v47
	v_add_f32_e32 v61, v67, v65
	v_pk_add_f32 v[56:57], v[60:61], v[68:69]
	s_nop 0
	v_pk_add_f32 v[56:57], v[56:57], v[56:57] op_sel_hi:[0,1]
	v_exp_f32_e32 v61, v55
	v_exp_f32_e32 v69, v59
	v_exp_f32_e32 v56, v43
	v_exp_f32_e32 v43, v45
	v_add_f32_e32 v55, v69, v61
	v_pk_add_f32 v[58:59], v[54:55], v[56:57]
	v_exp_f32_e32 v55, v48
	v_pk_add_f32 v[58:59], v[58:59], v[58:59] op_sel_hi:[0,1]
	v_exp_f32_e32 v58, v39
	v_exp_f32_e32 v48, v41
	v_add_f32_e32 v131, v55, v43
	v_exp_f32_e32 v57, v46
	v_pk_add_f32 v[44:45], v[130:131], v[58:59]
	v_exp_f32_e32 v59, v42
	v_pk_add_f32 v[44:45], v[44:45], v[44:45] op_sel_hi:[0,1]
	v_exp_f32_e32 v44, v3
	v_add_f32_e32 v139, v57, v48
	v_exp_f32_e32 v3, v38
	v_cvt_pk_bf16_f32 v38, v49, v4
	v_pk_add_f32 v[40:41], v[138:139], v[44:45]
	v_cvt_pk_bf16_f32 v39, v51, v52
	v_add_f32_e32 v141, v59, v3
	v_pk_add_f32 v[46:47], v[40:41], v[40:41] op_sel_hi:[0,1]
	v_exp_f32_e32 v46, v0
	v_cvt_pk_bf16_f32 v40, v53, v64
	v_cvt_pk_bf16_f32 v41, v65, v68
	v_cvt_pk_bf16_f32 v42, v61, v56
	v_cvt_pk_bf16_f32 v43, v43, v58
	v_cvt_pk_bf16_f32 v44, v48, v44
	s_nop 0
	v_pk_add_f32 v[0:1], v[140:141], v[46:47]
	v_cvt_pk_bf16_f32 v45, v3, v46
	v_cvt_pk_bf16_f32 v46, v143, v50
	v_cvt_pk_bf16_f32 v47, v142, v62
	v_cvt_pk_bf16_f32 v48, v63, v66
	v_cvt_pk_bf16_f32 v49, v67, v60
	v_cvt_pk_bf16_f32 v50, v69, v54
	v_cvt_pk_bf16_f32 v51, v55, v130
	v_cvt_pk_bf16_f32 v52, v57, v138
	v_cvt_pk_bf16_f32 v53, v59, v140
	ds_read_b64_tr_b16 v[54:55], v135 offset:26624
	ds_read_b64_tr_b16 v[56:57], v135 offset:28160
	ds_read_b64_tr_b16 v[58:59], v135 offset:26688
	ds_read_b64_tr_b16 v[60:61], v135 offset:28224
	ds_read_b64_tr_b16 v[62:63], v135 offset:29696
	ds_read_b64_tr_b16 v[64:65], v135 offset:31232
	ds_read_b64_tr_b16 v[66:67], v135 offset:29760
	ds_read_b64_tr_b16 v[68:69], v135 offset:31296
	v_add_f32_e32 v0, v0, v1
	s_waitcnt lgkmcnt(6)
	v_mfma_f32_32x32x16_bf16 v[6:21], v[54:57], v[38:41], v[6:21]
	s_waitcnt lgkmcnt(4)
	v_mfma_f32_32x32x16_bf16 v[22:37], v[58:61], v[38:41], v[22:37]
	ds_read_b64_tr_b16 v[38:39], v135 offset:32768
	ds_read_b64_tr_b16 v[40:41], v135 offset:34304
	ds_read_b64_tr_b16 v[56:57], v135 offset:34368
	ds_read_b64_tr_b16 v[54:55], v135 offset:32832
	s_waitcnt lgkmcnt(6)
	v_mfma_f32_32x32x16_bf16 v[6:21], v[62:65], v[42:45], v[6:21]
	s_waitcnt lgkmcnt(4)
	v_mfma_f32_32x32x16_bf16 v[22:37], v[66:69], v[42:45], v[22:37]
	ds_read_b64_tr_b16 v[42:43], v135 offset:35840
	ds_read_b64_tr_b16 v[44:45], v135 offset:37376
	ds_read_b64_tr_b16 v[60:61], v135 offset:37440
	ds_read_b64_tr_b16 v[58:59], v135 offset:35904
	s_waitcnt lgkmcnt(6)
	v_mfma_f32_32x32x16_bf16 v[6:21], v[38:41], v[46:49], v[6:21]
	s_waitcnt lgkmcnt(4)
	v_mfma_f32_32x32x16_bf16 v[22:37], v[54:57], v[46:49], v[22:37]
	s_waitcnt lgkmcnt(2)
	v_mfma_f32_32x32x16_bf16 v[6:21], v[42:45], v[50:53], v[6:21]
	s_waitcnt lgkmcnt(0)
	v_mfma_f32_32x32x16_bf16 v[22:37], v[58:61], v[50:53], v[22:37]
	v_add_f32_e32 v136, v136, v0
	s_cmp_lt_i32 s24, 1
	s_cbranch_scc1 .LBB0_167

.LBB0_177:
	v_exp_f32_e32 v143, v143
	v_exp_f32_e32 v145, v145
	v_exp_f32_e32 v4, v4
	v_exp_f32_e32 v48, v142
	v_exp_f32_e32 v52, v139
	v_add_f32_e32 v49, v145, v143
	v_exp_f32_e32 v64, v131
	v_pk_add_f32 v[50:51], v[48:49], v[4:5]
	v_exp_f32_e32 v49, v140
	v_pk_add_f32 v[50:51], v[50:51], v[50:51] op_sel_hi:[0,1]
	v_exp_f32_e32 v140, v144
	v_exp_f32_e32 v50, v130
	v_exp_f32_e32 v47, v47
	v_exp_f32_e32 v68, v43
	v_add_f32_e32 v53, v140, v49
	v_pk_add_f32 v[62:63], v[52:53], v[50:51]
	v_exp_f32_e32 v51, v138
	v_pk_add_f32 v[62:63], v[62:63], v[62:63] op_sel_hi:[0,1]
	v_exp_f32_e32 v53, v141
	v_exp_f32_e32 v62, v56
	v_exp_f32_e32 v40, v40
	v_exp_f32_e32 v130, v39
	v_add_f32_e32 v65, v53, v51
	v_pk_add_f32 v[66:67], v[64:65], v[62:63]
	v_exp_f32_e32 v63, v58
	v_pk_add_f32 v[66:67], v[66:67], v[66:67] op_sel_hi:[0,1]
	v_exp_f32_e32 v65, v60
	v_exp_f32_e32 v66, v54
	v_exp_f32_e32 v60, v57
	v_exp_f32_e32 v54, v46
	v_add_f32_e32 v61, v65, v63
	v_exp_f32_e32 v46, v44
	v_pk_add_f32 v[56:57], v[60:61], v[66:67]
	v_exp_f32_e32 v61, v55
	v_pk_add_f32 v[56:57], v[56:57], v[56:57] op_sel_hi:[0,1]
	v_exp_f32_e32 v67, v59
	v_exp_f32_e32 v56, v42
	v_add_f32_e32 v69, v47, v46
	v_exp_f32_e32 v138, v1
	v_add_f32_e32 v55, v67, v61
	v_pk_add_f32 v[58:59], v[54:55], v[56:57]
	v_exp_f32_e32 v55, v45
	v_pk_add_f32 v[58:59], v[58:59], v[58:59] op_sel_hi:[0,1]
	v_exp_f32_e32 v58, v38
	v_exp_f32_e32 v57, v41
	v_add_f32_e32 v131, v55, v40
	v_pk_add_f32 v[42:43], v[68:69], v[58:59]
	s_nop 0
	v_pk_add_f32 v[42:43], v[42:43], v[42:43] op_sel_hi:[0,1]
	v_exp_f32_e32 v42, v2
	s_nop 0
	v_pk_add_f32 v[38:39], v[130:131], v[42:43]
	s_nop 0
	v_pk_add_f32 v[44:45], v[38:39], v[38:39] op_sel_hi:[0,1]
	v_exp_f32_e32 v43, v3
	v_exp_f32_e32 v44, v0
	v_add_f32_e32 v139, v57, v43
	v_pk_add_f32 v[0:1], v[138:139], v[44:45]
	s_nop 0
	v_add_f32_e32 v69, v0, v1
	v_cvt_pk_bf16_f32 v0, v143, v4
	v_cvt_pk_bf16_f32 v1, v49, v50
	v_cvt_pk_bf16_f32 v2, v51, v62
	v_cvt_pk_bf16_f32 v3, v63, v66
	v_cvt_pk_bf16_f32 v38, v61, v56
	v_cvt_pk_bf16_f32 v39, v46, v58
	v_cvt_pk_bf16_f32 v40, v40, v42
	v_cvt_pk_bf16_f32 v41, v43, v44
	v_cvt_pk_bf16_f32 v42, v145, v48
	v_cvt_pk_bf16_f32 v43, v140, v52
	v_cvt_pk_bf16_f32 v44, v53, v64
	v_cvt_pk_bf16_f32 v45, v65, v60
	v_cvt_pk_bf16_f32 v46, v67, v54
	v_cvt_pk_bf16_f32 v47, v47, v68
	v_cvt_pk_bf16_f32 v48, v55, v130
	v_cvt_pk_bf16_f32 v49, v57, v138
	ds_read_b64_tr_b16 v[50:51], v135 offset:38912
	ds_read_b64_tr_b16 v[52:53], v135 offset:40448
	ds_read_b64_tr_b16 v[54:55], v135 offset:38976
	ds_read_b64_tr_b16 v[56:57], v135 offset:40512
	ds_read_b64_tr_b16 v[58:59], v135 offset:41984
	ds_read_b64_tr_b16 v[60:61], v135 offset:43520
	ds_read_b64_tr_b16 v[62:63], v135 offset:42048
	ds_read_b64_tr_b16 v[64:65], v135 offset:43584
	s_waitcnt lgkmcnt(6)
	v_mfma_f32_32x32x16_bf16 v[6:21], v[50:53], v[0:3], v[6:21]
	s_waitcnt lgkmcnt(4)
	v_mfma_f32_32x32x16_bf16 v[22:37], v[54:57], v[0:3], v[22:37]
	ds_read_b64_tr_b16 v[0:1], v135 offset:45056
	ds_read_b64_tr_b16 v[2:3], v135 offset:46592
	ds_read_b64_tr_b16 v[52:53], v135 offset:46656
	ds_read_b64_tr_b16 v[50:51], v135 offset:45120
	s_waitcnt lgkmcnt(6)
	v_mfma_f32_32x32x16_bf16 v[6:21], v[58:61], v[38:41], v[6:21]
	s_waitcnt lgkmcnt(4)
	v_mfma_f32_32x32x16_bf16 v[22:37], v[62:65], v[38:41], v[22:37]
	ds_read_b64_tr_b16 v[38:39], v135 offset:48128
	ds_read_b64_tr_b16 v[40:41], v135 offset:49664
	ds_read_b64_tr_b16 v[56:57], v135 offset:49728
	ds_read_b64_tr_b16 v[54:55], v135 offset:48192
	s_waitcnt lgkmcnt(6)
	v_mfma_f32_32x32x16_bf16 v[6:21], v[0:3], v[42:45], v[6:21]
	s_waitcnt lgkmcnt(4)
	v_mfma_f32_32x32x16_bf16 v[22:37], v[50:53], v[42:45], v[22:37]
	s_waitcnt lgkmcnt(2)
	v_mfma_f32_32x32x16_bf16 v[6:21], v[38:41], v[46:49], v[6:21]
	s_waitcnt lgkmcnt(0)
	v_mfma_f32_32x32x16_bf16 v[22:37], v[54:57], v[46:49], v[22:37]
	v_add_f32_e32 v136, v136, v69
	s_andn2_b64 vcc, exec, s[16:17]
	s_cbranch_vccnz .LBB0_181

.LBB0_198:
	v_exp_f32_e32 v3, v128
	v_exp_f32_e32 v128, v130
	v_exp_f32_e32 v50, v129
	v_exp_f32_e32 v4, v131
	v_exp_f32_e32 v126, v126
	v_add_f32_e32 v51, v3, v128
	v_exp_f32_e32 v62, v125
	v_pk_add_f32 v[52:53], v[50:51], v[4:5]
	v_exp_f32_e32 v51, v124
	v_pk_add_f32 v[52:53], v[52:53], v[52:53] op_sel_hi:[0,1]
	v_exp_f32_e32 v52, v127
	v_exp_f32_e32 v66, v121
	v_add_f32_e32 v63, v51, v126
	v_pk_add_f32 v[64:65], v[62:63], v[52:53]
	s_nop 0
	v_pk_add_f32 v[64:65], v[64:65], v[64:65] op_sel_hi:[0,1]
	v_exp_f32_e32 v53, v120
	v_exp_f32_e32 v63, v122
	v_exp_f32_e32 v64, v123
	v_exp_f32_e32 v120, v59
	v_add_f32_e32 v67, v53, v63
	v_pk_add_f32 v[68:69], v[66:67], v[64:65]
	v_exp_f32_e32 v65, v58
	v_pk_add_f32 v[68:69], v[68:69], v[68:69] op_sel_hi:[0,1]
	v_exp_f32_e32 v67, v60
	v_exp_f32_e32 v68, v61
	v_exp_f32_e32 v60, v55
	v_add_f32_e32 v121, v65, v67
	v_pk_add_f32 v[58:59], v[120:121], v[68:69]
	v_exp_f32_e32 v69, v54
	v_pk_add_f32 v[58:59], v[58:59], v[58:59] op_sel_hi:[0,1]
	v_exp_f32_e32 v121, v56
	v_exp_f32_e32 v58, v57
	v_exp_f32_e32 v56, v47
	v_add_f32_e32 v61, v69, v121
	v_pk_add_f32 v[54:55], v[60:61], v[58:59]
	v_exp_f32_e32 v59, v46
	v_pk_add_f32 v[54:55], v[54:55], v[54:55] op_sel_hi:[0,1]
	v_exp_f32_e32 v61, v48
	v_exp_f32_e32 v54, v49
	v_exp_f32_e32 v48, v39
	v_add_f32_e32 v57, v59, v61
	v_pk_add_f32 v[46:47], v[56:57], v[54:55]
	v_exp_f32_e32 v55, v42
	v_pk_add_f32 v[122:123], v[46:47], v[46:47] op_sel_hi:[0,1]
	v_exp_f32_e32 v57, v44
	v_exp_f32_e32 v46, v43
	v_exp_f32_e32 v122, v45
	v_exp_f32_e32 v45, v38
	v_add_f32_e32 v47, v55, v57
	v_pk_add_f32 v[42:43], v[46:47], v[122:123]
	s_nop 0
	v_pk_add_f32 v[124:125], v[42:43], v[42:43] op_sel_hi:[0,1]
	v_exp_f32_e32 v123, v40
	v_exp_f32_e32 v124, v41
	v_add_f32_e32 v49, v45, v123
	v_pk_add_f32 v[38:39], v[48:49], v[124:125]
	s_nop 0
	v_add_f32_e32 v125, v38, v39
	v_cvt_pk_bf16_f32 v38, v3, v50
	v_add_u32_e32 v3, s5, v135
	v_cvt_pk_bf16_f32 v39, v51, v62
	v_cvt_pk_bf16_f32 v40, v53, v66
	v_cvt_pk_bf16_f32 v41, v65, v120
	v_cvt_pk_bf16_f32 v42, v69, v60
	v_cvt_pk_bf16_f32 v43, v59, v56
	v_cvt_pk_bf16_f32 v44, v55, v46
	v_cvt_pk_bf16_f32 v45, v45, v48
	v_cvt_pk_bf16_f32 v46, v128, v4
	v_cvt_pk_bf16_f32 v47, v126, v52
	v_cvt_pk_bf16_f32 v48, v63, v64
	v_cvt_pk_bf16_f32 v49, v67, v68
	v_cvt_pk_bf16_f32 v50, v121, v58
	v_cvt_pk_bf16_f32 v51, v61, v54
	v_cvt_pk_bf16_f32 v52, v57, v122
	v_cvt_pk_bf16_f32 v53, v123, v124
	ds_read_b64_tr_b16 v[54:55], v3 offset:26624
	ds_read_b64_tr_b16 v[56:57], v3 offset:28160
	ds_read_b64_tr_b16 v[58:59], v3 offset:26688
	ds_read_b64_tr_b16 v[60:61], v3 offset:28224
	ds_read_b64_tr_b16 v[62:63], v3 offset:29696
	ds_read_b64_tr_b16 v[64:65], v3 offset:31232
	ds_read_b64_tr_b16 v[66:67], v3 offset:29760
	ds_read_b64_tr_b16 v[68:69], v3 offset:31296
	s_waitcnt lgkmcnt(6)
	v_mfma_f32_32x32x16_bf16 v[6:21], v[54:57], v[38:41], v[6:21]
	s_waitcnt lgkmcnt(4)
	v_mfma_f32_32x32x16_bf16 v[22:37], v[58:61], v[38:41], v[22:37]
	ds_read_b64_tr_b16 v[38:39], v3 offset:32768
	ds_read_b64_tr_b16 v[40:41], v3 offset:34304
	ds_read_b64_tr_b16 v[56:57], v3 offset:34368
	ds_read_b64_tr_b16 v[54:55], v3 offset:32832
	s_waitcnt lgkmcnt(6)
	v_mfma_f32_32x32x16_bf16 v[6:21], v[62:65], v[42:45], v[6:21]
	s_waitcnt lgkmcnt(4)
	v_mfma_f32_32x32x16_bf16 v[22:37], v[66:69], v[42:45], v[22:37]
	ds_read_b64_tr_b16 v[42:43], v3 offset:35840
	ds_read_b64_tr_b16 v[44:45], v3 offset:37376
	ds_read_b64_tr_b16 v[60:61], v3 offset:37440
	ds_read_b64_tr_b16 v[58:59], v3 offset:35904
	s_waitcnt lgkmcnt(6)
	v_mfma_f32_32x32x16_bf16 v[6:21], v[38:41], v[46:49], v[6:21]
	s_waitcnt lgkmcnt(4)
	v_mfma_f32_32x32x16_bf16 v[22:37], v[54:57], v[46:49], v[22:37]
	s_waitcnt lgkmcnt(2)
	v_mfma_f32_32x32x16_bf16 v[6:21], v[42:45], v[50:53], v[6:21]
	s_waitcnt lgkmcnt(0)
	v_mfma_f32_32x32x16_bf16 v[22:37], v[58:61], v[50:53], v[22:37]
	v_add_f32_e32 v136, v136, v125
	s_cmp_eq_u32 s23, 0
	s_cbranch_scc1 .LBB0_202

.LBB0_212:
	v_exp_f32_e32 v3, v128
	v_exp_f32_e32 v128, v130
	v_exp_f32_e32 v50, v129
	v_exp_f32_e32 v4, v131
	v_exp_f32_e32 v126, v126
	v_add_f32_e32 v51, v3, v128
	v_exp_f32_e32 v62, v125
	v_pk_add_f32 v[52:53], v[50:51], v[4:5]
	v_exp_f32_e32 v51, v124
	v_pk_add_f32 v[52:53], v[52:53], v[52:53] op_sel_hi:[0,1]
	v_exp_f32_e32 v52, v127
	v_exp_f32_e32 v66, v121
	v_add_f32_e32 v63, v51, v126
	v_pk_add_f32 v[64:65], v[62:63], v[52:53]
	s_nop 0
	v_pk_add_f32 v[64:65], v[64:65], v[64:65] op_sel_hi:[0,1]
	v_exp_f32_e32 v53, v120
	v_exp_f32_e32 v63, v122
	v_exp_f32_e32 v64, v123
	v_exp_f32_e32 v120, v59
	v_add_f32_e32 v67, v53, v63
	v_pk_add_f32 v[68:69], v[66:67], v[64:65]
	v_exp_f32_e32 v65, v58
	v_pk_add_f32 v[68:69], v[68:69], v[68:69] op_sel_hi:[0,1]
	v_exp_f32_e32 v67, v60
	v_exp_f32_e32 v68, v61
	v_exp_f32_e32 v60, v55
	v_add_f32_e32 v121, v65, v67
	v_pk_add_f32 v[58:59], v[120:121], v[68:69]
	v_exp_f32_e32 v69, v54
	v_pk_add_f32 v[58:59], v[58:59], v[58:59] op_sel_hi:[0,1]
	v_exp_f32_e32 v121, v56
	v_exp_f32_e32 v58, v57
	v_exp_f32_e32 v56, v47
	v_add_f32_e32 v61, v69, v121
	v_pk_add_f32 v[54:55], v[60:61], v[58:59]
	v_exp_f32_e32 v59, v46
	v_pk_add_f32 v[54:55], v[54:55], v[54:55] op_sel_hi:[0,1]
	v_exp_f32_e32 v61, v48
	v_exp_f32_e32 v54, v49
	v_exp_f32_e32 v48, v39
	v_add_f32_e32 v57, v59, v61
	v_pk_add_f32 v[46:47], v[56:57], v[54:55]
	v_exp_f32_e32 v55, v42
	v_pk_add_f32 v[122:123], v[46:47], v[46:47] op_sel_hi:[0,1]
	v_exp_f32_e32 v57, v44
	v_exp_f32_e32 v46, v43
	v_exp_f32_e32 v122, v45
	v_exp_f32_e32 v45, v38
	v_add_f32_e32 v47, v55, v57
	v_pk_add_f32 v[42:43], v[46:47], v[122:123]
	s_nop 0
	v_pk_add_f32 v[124:125], v[42:43], v[42:43] op_sel_hi:[0,1]
	v_exp_f32_e32 v123, v40
	v_exp_f32_e32 v124, v41
	v_add_f32_e32 v49, v45, v123
	v_pk_add_f32 v[38:39], v[48:49], v[124:125]
	s_nop 0
	v_add_f32_e32 v125, v38, v39
	v_cvt_pk_bf16_f32 v38, v3, v50
	v_add_u32_e32 v3, s24, v135
	v_cvt_pk_bf16_f32 v39, v51, v62
	v_cvt_pk_bf16_f32 v40, v53, v66
	v_cvt_pk_bf16_f32 v41, v65, v120
	v_cvt_pk_bf16_f32 v42, v69, v60
	v_cvt_pk_bf16_f32 v43, v59, v56
	v_cvt_pk_bf16_f32 v44, v55, v46
	v_cvt_pk_bf16_f32 v45, v45, v48
	v_cvt_pk_bf16_f32 v46, v128, v4
	v_cvt_pk_bf16_f32 v47, v126, v52
	v_cvt_pk_bf16_f32 v48, v63, v64
	v_cvt_pk_bf16_f32 v49, v67, v68
	v_cvt_pk_bf16_f32 v50, v121, v58
	v_cvt_pk_bf16_f32 v51, v61, v54
	v_cvt_pk_bf16_f32 v52, v57, v122
	v_cvt_pk_bf16_f32 v53, v123, v124
	ds_read_b64_tr_b16 v[54:55], v3 offset:26624
	ds_read_b64_tr_b16 v[56:57], v3 offset:28160
	ds_read_b64_tr_b16 v[58:59], v3 offset:26688
	ds_read_b64_tr_b16 v[60:61], v3 offset:28224
	ds_read_b64_tr_b16 v[62:63], v3 offset:29696
	ds_read_b64_tr_b16 v[64:65], v3 offset:31232
	ds_read_b64_tr_b16 v[66:67], v3 offset:29760
	ds_read_b64_tr_b16 v[68:69], v3 offset:31296
	s_waitcnt lgkmcnt(6)
	v_mfma_f32_32x32x16_bf16 v[6:21], v[54:57], v[38:41], v[6:21]
	s_waitcnt lgkmcnt(4)
	v_mfma_f32_32x32x16_bf16 v[22:37], v[58:61], v[38:41], v[22:37]
	ds_read_b64_tr_b16 v[38:39], v3 offset:32768
	ds_read_b64_tr_b16 v[40:41], v3 offset:34304
	ds_read_b64_tr_b16 v[56:57], v3 offset:34368
	ds_read_b64_tr_b16 v[54:55], v3 offset:32832
	s_waitcnt lgkmcnt(6)
	v_mfma_f32_32x32x16_bf16 v[6:21], v[62:65], v[42:45], v[6:21]
	s_waitcnt lgkmcnt(4)
	v_mfma_f32_32x32x16_bf16 v[22:37], v[66:69], v[42:45], v[22:37]
	ds_read_b64_tr_b16 v[42:43], v3 offset:35840
	ds_read_b64_tr_b16 v[44:45], v3 offset:37376
	ds_read_b64_tr_b16 v[60:61], v3 offset:37440
	ds_read_b64_tr_b16 v[58:59], v3 offset:35904
	s_waitcnt lgkmcnt(6)
	v_mfma_f32_32x32x16_bf16 v[6:21], v[38:41], v[46:49], v[6:21]
	s_waitcnt lgkmcnt(4)
	v_mfma_f32_32x32x16_bf16 v[22:37], v[54:57], v[46:49], v[22:37]
	s_waitcnt lgkmcnt(2)
	v_mfma_f32_32x32x16_bf16 v[6:21], v[42:45], v[50:53], v[6:21]
	s_waitcnt lgkmcnt(0)
	v_mfma_f32_32x32x16_bf16 v[22:37], v[58:61], v[50:53], v[22:37]
	v_add_f32_e32 v136, v136, v125
	s_andn2_b64 vcc, exec, s[16:17]
	s_cbranch_vccnz .LBB0_187

.LBB0_639:
	v_exp_f32_e32 v100, v160
	v_exp_f32_e32 v101, v2
	v_exp_f32_e32 v4, v161
	v_exp_f32_e32 v80, v3
	v_exp_f32_e32 v102, v6
	v_add_f32_e32 v81, v101, v100
	v_exp_f32_e32 v82, v7
	v_pk_add_f32 v[2:3], v[80:81], v[4:5]
	v_exp_f32_e32 v81, v164
	v_pk_add_f32 v[2:3], v[2:3], v[2:3] op_sel_hi:[0,1]
	v_exp_f32_e32 v2, v165
	v_exp_f32_e32 v84, v11
	v_add_f32_e32 v83, v102, v81
	v_exp_f32_e32 v86, v157
	v_pk_add_f32 v[6:7], v[82:83], v[2:3]
	v_exp_f32_e32 v3, v168
	v_pk_add_f32 v[6:7], v[6:7], v[6:7] op_sel_hi:[0,1]
	v_exp_f32_e32 v83, v10
	v_exp_f32_e32 v6, v169
	v_exp_f32_e32 v90, v15
	v_exp_f32_e32 v92, v13
	v_add_f32_e32 v85, v83, v3
	v_pk_add_f32 v[10:11], v[84:85], v[6:7]
	v_exp_f32_e32 v7, v172
	v_pk_add_f32 v[10:11], v[10:11], v[10:11] op_sel_hi:[0,1]
	v_exp_f32_e32 v85, v156
	v_exp_f32_e32 v10, v173
	v_exp_f32_e32 v94, v9
	v_exp_f32_e32 v98, v1
	v_add_f32_e32 v87, v85, v7
	v_pk_add_f32 v[88:89], v[86:87], v[10:11]
	v_exp_f32_e32 v11, v170
	v_pk_add_f32 v[88:89], v[88:89], v[88:89] op_sel_hi:[0,1]
	v_exp_f32_e32 v87, v14
	v_exp_f32_e32 v88, v171
	v_add_f32_e32 v91, v87, v11
	v_pk_add_f32 v[14:15], v[90:91], v[88:89]
	v_exp_f32_e32 v89, v166
	v_pk_add_f32 v[14:15], v[14:15], v[14:15] op_sel_hi:[0,1]
	v_exp_f32_e32 v91, v12
	v_exp_f32_e32 v14, v167
	v_add_f32_e32 v93, v91, v89
	v_pk_add_f32 v[12:13], v[92:93], v[14:15]
	v_exp_f32_e32 v15, v162
	v_pk_add_f32 v[12:13], v[12:13], v[12:13] op_sel_hi:[0,1]
	v_exp_f32_e32 v93, v8
	v_exp_f32_e32 v12, v163
	v_add_f32_e32 v95, v93, v15
	v_pk_add_f32 v[8:9], v[94:95], v[12:13]
	v_exp_f32_e32 v95, v0
	v_pk_add_f32 v[96:97], v[8:9], v[8:9] op_sel_hi:[0,1]
	v_exp_f32_e32 v9, v158
	v_exp_f32_e32 v96, v159
	v_add_f32_e32 v99, v95, v9
	v_pk_add_f32 v[0:1], v[98:99], v[96:97]
	s_nop 0
	v_add_f32_e32 v160, v0, v1
	v_cvt_pk_bf16_f32 v0, v100, v4
	v_cvt_pk_bf16_f32 v1, v81, v2
	v_cvt_pk_bf16_f32 v2, v3, v6
	v_cvt_pk_bf16_f32 v3, v7, v10
	v_cvt_pk_bf16_f32 v6, v11, v88
	v_cvt_pk_bf16_f32 v7, v89, v14
	v_cvt_pk_bf16_f32 v8, v15, v12
	v_cvt_pk_bf16_f32 v9, v9, v96
	v_cvt_pk_bf16_f32 v10, v101, v80
	v_cvt_pk_bf16_f32 v11, v102, v82
	v_cvt_pk_bf16_f32 v12, v83, v84
	v_cvt_pk_bf16_f32 v13, v85, v86
	v_cvt_pk_bf16_f32 v80, v87, v90
	v_cvt_pk_bf16_f32 v81, v91, v92
	v_cvt_pk_bf16_f32 v82, v93, v94
	v_cvt_pk_bf16_f32 v83, v95, v98
	ds_read_b64_tr_b16 v[84:85], v181 offset:34816
	ds_read_b64_tr_b16 v[86:87], v181 offset:37376
	ds_read_b64_tr_b16 v[88:89], v181 offset:34880
	ds_read_b64_tr_b16 v[90:91], v181 offset:37440
	ds_read_b64_tr_b16 v[92:93], v181 offset:34944
	ds_read_b64_tr_b16 v[94:95], v181 offset:37504
	ds_read_b64_tr_b16 v[96:97], v181 offset:35008
	ds_read_b64_tr_b16 v[98:99], v181 offset:37568
	ds_read_b64_tr_b16 v[100:101], v181 offset:39936
	ds_read_b64_tr_b16 v[102:103], v181 offset:42496
	ds_read_b64_tr_b16 v[104:105], v181 offset:40000
	ds_read_b64_tr_b16 v[106:107], v181 offset:42560
	ds_read_b64_tr_b16 v[108:109], v181 offset:40064
	ds_read_b64_tr_b16 v[110:111], v181 offset:42624
	ds_read_b64_tr_b16 v[156:157], v181 offset:40128
	ds_read_b64_tr_b16 v[158:159], v181 offset:42688
	s_waitcnt lgkmcnt(14)
	v_mfma_f32_32x32x16_bf16 v[64:79], v[84:87], v[0:3], v[64:79]
	s_waitcnt lgkmcnt(12)
	v_mfma_f32_32x32x16_bf16 v[48:63], v[88:91], v[0:3], v[48:63]
	s_waitcnt lgkmcnt(10)
	v_mfma_f32_32x32x16_bf16 v[32:47], v[92:95], v[0:3], v[32:47]
	s_waitcnt lgkmcnt(8)
	v_mfma_f32_32x32x16_bf16 v[16:31], v[96:99], v[0:3], v[16:31]
	ds_read_b64_tr_b16 v[0:1], v181 offset:45056
	ds_read_b64_tr_b16 v[84:85], v181 offset:45120
	ds_read_b64_tr_b16 v[88:89], v181 offset:45184
	ds_read_b64_tr_b16 v[92:93], v181 offset:45248
	ds_read_b64_tr_b16 v[2:3], v181 offset:47616
	ds_read_b64_tr_b16 v[86:87], v181 offset:47680
	ds_read_b64_tr_b16 v[90:91], v181 offset:47744
	ds_read_b64_tr_b16 v[94:95], v181 offset:47808
	s_waitcnt lgkmcnt(14)
	v_mfma_f32_32x32x16_bf16 v[64:79], v[100:103], v[6:9], v[64:79]
	s_waitcnt lgkmcnt(12)
	v_mfma_f32_32x32x16_bf16 v[48:63], v[104:107], v[6:9], v[48:63]
	s_waitcnt lgkmcnt(10)
	v_mfma_f32_32x32x16_bf16 v[32:47], v[108:111], v[6:9], v[32:47]
	s_waitcnt lgkmcnt(8)
	v_mfma_f32_32x32x16_bf16 v[16:31], v[156:159], v[6:9], v[16:31]
	ds_read_b64_tr_b16 v[6:7], v181 offset:50176
	ds_read_b64_tr_b16 v[96:97], v181 offset:50240
	ds_read_b64_tr_b16 v[100:101], v181 offset:50304
	ds_read_b64_tr_b16 v[104:105], v181 offset:50368
	ds_read_b64_tr_b16 v[8:9], v181 offset:52736
	ds_read_b64_tr_b16 v[98:99], v181 offset:52800
	ds_read_b64_tr_b16 v[102:103], v181 offset:52864
	ds_read_b64_tr_b16 v[106:107], v181 offset:52928
	s_waitcnt lgkmcnt(11)
	v_mfma_f32_32x32x16_bf16 v[64:79], v[0:3], v[10:13], v[64:79]
	s_waitcnt lgkmcnt(10)
	v_mfma_f32_32x32x16_bf16 v[48:63], v[84:87], v[10:13], v[48:63]
	s_waitcnt lgkmcnt(9)
	v_mfma_f32_32x32x16_bf16 v[32:47], v[88:91], v[10:13], v[32:47]
	s_waitcnt lgkmcnt(8)
	v_mfma_f32_32x32x16_bf16 v[16:31], v[92:95], v[10:13], v[16:31]
	s_waitcnt lgkmcnt(3)
	v_mfma_f32_32x32x16_bf16 v[64:79], v[6:9], v[80:83], v[64:79]
	s_waitcnt lgkmcnt(2)
	v_mfma_f32_32x32x16_bf16 v[48:63], v[96:99], v[80:83], v[48:63]
	s_waitcnt lgkmcnt(1)
	v_mfma_f32_32x32x16_bf16 v[32:47], v[100:103], v[80:83], v[32:47]
	s_waitcnt lgkmcnt(0)
	v_mfma_f32_32x32x16_bf16 v[16:31], v[104:107], v[80:83], v[16:31]
	v_add_f32_e32 v205, v205, v160
	s_cmp_lt_i32 s92, 1
	s_cbranch_scc0 .LBB0_223
	s_branch .LBB0_224

.LBB0_650:
	v_exp_f32_e32 v100, v160
	v_exp_f32_e32 v101, v2
	v_exp_f32_e32 v4, v161
	v_exp_f32_e32 v80, v3
	v_exp_f32_e32 v102, v6
	v_add_f32_e32 v81, v101, v100
	v_exp_f32_e32 v82, v7
	v_pk_add_f32 v[2:3], v[80:81], v[4:5]
	v_exp_f32_e32 v81, v164
	v_pk_add_f32 v[2:3], v[2:3], v[2:3] op_sel_hi:[0,1]
	v_exp_f32_e32 v2, v165
	v_exp_f32_e32 v84, v11
	v_add_f32_e32 v83, v102, v81
	v_exp_f32_e32 v86, v157
	v_pk_add_f32 v[6:7], v[82:83], v[2:3]
	v_exp_f32_e32 v3, v168
	v_pk_add_f32 v[6:7], v[6:7], v[6:7] op_sel_hi:[0,1]
	v_exp_f32_e32 v83, v10
	v_exp_f32_e32 v6, v169
	v_exp_f32_e32 v90, v15
	v_exp_f32_e32 v92, v13
	v_add_f32_e32 v85, v83, v3
	v_pk_add_f32 v[10:11], v[84:85], v[6:7]
	v_exp_f32_e32 v7, v172
	v_pk_add_f32 v[10:11], v[10:11], v[10:11] op_sel_hi:[0,1]
	v_exp_f32_e32 v85, v156
	v_exp_f32_e32 v10, v173
	v_exp_f32_e32 v94, v9
	v_exp_f32_e32 v98, v1
	v_add_f32_e32 v87, v85, v7
	v_pk_add_f32 v[88:89], v[86:87], v[10:11]
	v_exp_f32_e32 v11, v170
	v_pk_add_f32 v[88:89], v[88:89], v[88:89] op_sel_hi:[0,1]
	v_exp_f32_e32 v87, v14
	v_exp_f32_e32 v88, v171
	v_add_f32_e32 v91, v87, v11
	v_pk_add_f32 v[14:15], v[90:91], v[88:89]
	v_exp_f32_e32 v89, v166
	v_pk_add_f32 v[14:15], v[14:15], v[14:15] op_sel_hi:[0,1]
	v_exp_f32_e32 v91, v12
	v_exp_f32_e32 v14, v167
	v_add_f32_e32 v93, v91, v89
	v_pk_add_f32 v[12:13], v[92:93], v[14:15]
	v_exp_f32_e32 v15, v162
	v_pk_add_f32 v[12:13], v[12:13], v[12:13] op_sel_hi:[0,1]
	v_exp_f32_e32 v93, v8
	v_exp_f32_e32 v12, v163
	v_add_f32_e32 v95, v93, v15
	v_pk_add_f32 v[8:9], v[94:95], v[12:13]
	v_exp_f32_e32 v95, v0
	v_pk_add_f32 v[96:97], v[8:9], v[8:9] op_sel_hi:[0,1]
	v_exp_f32_e32 v9, v158
	v_exp_f32_e32 v96, v159
	v_add_f32_e32 v99, v95, v9
	v_pk_add_f32 v[0:1], v[98:99], v[96:97]
	s_nop 0
	v_add_f32_e32 v160, v0, v1
	v_cvt_pk_bf16_f32 v0, v100, v4
	v_cvt_pk_bf16_f32 v1, v81, v2
	v_cvt_pk_bf16_f32 v2, v3, v6
	v_cvt_pk_bf16_f32 v3, v7, v10
	v_cvt_pk_bf16_f32 v6, v11, v88
	v_cvt_pk_bf16_f32 v7, v89, v14
	v_cvt_pk_bf16_f32 v8, v15, v12
	v_cvt_pk_bf16_f32 v9, v9, v96
	v_cvt_pk_bf16_f32 v10, v101, v80
	v_cvt_pk_bf16_f32 v11, v102, v82
	v_cvt_pk_bf16_f32 v12, v83, v84
	v_cvt_pk_bf16_f32 v13, v85, v86
	v_cvt_pk_bf16_f32 v80, v87, v90
	v_cvt_pk_bf16_f32 v81, v91, v92
	v_cvt_pk_bf16_f32 v82, v93, v94
	v_cvt_pk_bf16_f32 v83, v95, v98
	ds_read_b64_tr_b16 v[84:85], v181 offset:55296
	ds_read_b64_tr_b16 v[86:87], v181 offset:57856
	ds_read_b64_tr_b16 v[88:89], v181 offset:55360
	ds_read_b64_tr_b16 v[90:91], v181 offset:57920
	ds_read_b64_tr_b16 v[92:93], v181 offset:55424
	ds_read_b64_tr_b16 v[94:95], v181 offset:57984
	ds_read_b64_tr_b16 v[96:97], v181 offset:55488
	ds_read_b64_tr_b16 v[98:99], v181 offset:58048
	ds_read_b64_tr_b16 v[100:101], v181 offset:60416
	ds_read_b64_tr_b16 v[102:103], v181 offset:62976
	ds_read_b64_tr_b16 v[104:105], v181 offset:60480
	ds_read_b64_tr_b16 v[106:107], v181 offset:63040
	ds_read_b64_tr_b16 v[108:109], v181 offset:60544
	ds_read_b64_tr_b16 v[110:111], v181 offset:63104
	ds_read_b64_tr_b16 v[156:157], v181 offset:60608
	ds_read_b64_tr_b16 v[158:159], v181 offset:63168
	s_waitcnt lgkmcnt(14)
	v_mfma_f32_32x32x16_bf16 v[64:79], v[84:87], v[0:3], v[64:79]
	s_waitcnt lgkmcnt(12)
	v_mfma_f32_32x32x16_bf16 v[48:63], v[88:91], v[0:3], v[48:63]
	s_waitcnt lgkmcnt(10)
	v_mfma_f32_32x32x16_bf16 v[32:47], v[92:95], v[0:3], v[32:47]
	s_waitcnt lgkmcnt(8)
	v_mfma_f32_32x32x16_bf16 v[16:31], v[96:99], v[0:3], v[16:31]
	ds_read_b64_tr_b16 v[0:1], v224 offset:30720
	ds_read_b64_tr_b16 v[84:85], v224 offset:30784
	ds_read_b64_tr_b16 v[88:89], v224 offset:30848
	ds_read_b64_tr_b16 v[92:93], v224 offset:30912
	ds_read_b64_tr_b16 v[2:3], v224 offset:33280
	ds_read_b64_tr_b16 v[86:87], v224 offset:33344
	ds_read_b64_tr_b16 v[90:91], v224 offset:33408
	ds_read_b64_tr_b16 v[94:95], v224 offset:33472
	s_waitcnt lgkmcnt(14)
	v_mfma_f32_32x32x16_bf16 v[64:79], v[100:103], v[6:9], v[64:79]
	s_waitcnt lgkmcnt(12)
	v_mfma_f32_32x32x16_bf16 v[48:63], v[104:107], v[6:9], v[48:63]
	s_waitcnt lgkmcnt(10)
	v_mfma_f32_32x32x16_bf16 v[32:47], v[108:111], v[6:9], v[32:47]
	s_waitcnt lgkmcnt(8)
	v_mfma_f32_32x32x16_bf16 v[16:31], v[156:159], v[6:9], v[16:31]
	ds_read_b64_tr_b16 v[6:7], v224 offset:35840
	ds_read_b64_tr_b16 v[96:97], v224 offset:35904
	ds_read_b64_tr_b16 v[100:101], v224 offset:35968
	ds_read_b64_tr_b16 v[104:105], v224 offset:36032
	ds_read_b64_tr_b16 v[8:9], v224 offset:38400
	ds_read_b64_tr_b16 v[98:99], v224 offset:38464
	ds_read_b64_tr_b16 v[102:103], v224 offset:38528
	ds_read_b64_tr_b16 v[106:107], v224 offset:38592
	s_waitcnt lgkmcnt(11)
	v_mfma_f32_32x32x16_bf16 v[64:79], v[0:3], v[10:13], v[64:79]
	s_waitcnt lgkmcnt(10)
	v_mfma_f32_32x32x16_bf16 v[48:63], v[84:87], v[10:13], v[48:63]
	s_waitcnt lgkmcnt(9)
	v_mfma_f32_32x32x16_bf16 v[32:47], v[88:91], v[10:13], v[32:47]
	s_waitcnt lgkmcnt(8)
	v_mfma_f32_32x32x16_bf16 v[16:31], v[92:95], v[10:13], v[16:31]
	s_waitcnt lgkmcnt(3)
	v_mfma_f32_32x32x16_bf16 v[64:79], v[6:9], v[80:83], v[64:79]
	s_waitcnt lgkmcnt(2)
	v_mfma_f32_32x32x16_bf16 v[48:63], v[96:99], v[80:83], v[48:63]
	s_waitcnt lgkmcnt(1)
	v_mfma_f32_32x32x16_bf16 v[32:47], v[100:103], v[80:83], v[32:47]
	s_waitcnt lgkmcnt(0)
	v_mfma_f32_32x32x16_bf16 v[16:31], v[104:107], v[80:83], v[16:31]
	v_add_f32_e32 v205, v205, v160
	s_andn2_b64 vcc, exec, s[14:15]
	s_cbranch_vccnz .LBB0_219

.LBB0_671:
	v_exp_f32_e32 v108, v211
	v_exp_f32_e32 v109, v212
	v_exp_f32_e32 v4, v4
	v_exp_f32_e32 v88, v210
	v_exp_f32_e32 v110, v209
	v_add_f32_e32 v89, v109, v108
	v_exp_f32_e32 v92, v207
	v_pk_add_f32 v[90:91], v[88:89], v[4:5]
	v_exp_f32_e32 v89, v208
	v_pk_add_f32 v[90:91], v[90:91], v[90:91] op_sel_hi:[0,1]
	v_exp_f32_e32 v90, v206
	v_exp_f32_e32 v98, v98
	v_add_f32_e32 v93, v110, v89
	v_exp_f32_e32 v14, v14
	v_pk_add_f32 v[94:95], v[92:93], v[90:91]
	v_exp_f32_e32 v91, v99
	v_pk_add_f32 v[94:95], v[94:95], v[94:95] op_sel_hi:[0,1]
	v_exp_f32_e32 v93, v100
	v_exp_f32_e32 v94, v97
	v_exp_f32_e32 v102, v10
	v_exp_f32_e32 v106, v6
	v_add_f32_e32 v99, v93, v91
	v_pk_add_f32 v[100:101], v[98:99], v[94:95]
	v_exp_f32_e32 v95, v96
	v_pk_add_f32 v[100:101], v[100:101], v[100:101] op_sel_hi:[0,1]
	v_exp_f32_e32 v99, v86
	v_exp_f32_e32 v100, v84
	v_exp_f32_e32 v96, v87
	v_exp_f32_e32 v84, v82
	v_add_f32_e32 v97, v99, v95
	v_pk_add_f32 v[86:87], v[96:97], v[100:101]
	s_nop 0
	v_pk_add_f32 v[86:87], v[86:87], v[86:87] op_sel_hi:[0,1]
	v_exp_f32_e32 v97, v83
	v_exp_f32_e32 v101, v85
	v_exp_f32_e32 v86, v80
	v_add_f32_e32 v85, v101, v97
	v_pk_add_f32 v[82:83], v[84:85], v[86:87]
	v_exp_f32_e32 v85, v15
	v_pk_add_f32 v[82:83], v[82:83], v[82:83] op_sel_hi:[0,1]
	v_exp_f32_e32 v87, v81
	v_exp_f32_e32 v82, v12
	v_exp_f32_e32 v12, v11
	v_add_f32_e32 v15, v87, v85
	v_pk_add_f32 v[80:81], v[14:15], v[82:83]
	v_exp_f32_e32 v15, v13
	v_pk_add_f32 v[80:81], v[80:81], v[80:81] op_sel_hi:[0,1]
	v_exp_f32_e32 v80, v8
	v_exp_f32_e32 v13, v7
	v_add_f32_e32 v103, v15, v12
	v_pk_add_f32 v[10:11], v[102:103], v[80:81]
	s_nop 0
	v_pk_add_f32 v[104:105], v[10:11], v[10:11] op_sel_hi:[0,1]
	v_exp_f32_e32 v103, v9
	v_exp_f32_e32 v104, v3
	v_add_f32_e32 v107, v103, v13
	v_pk_add_f32 v[6:7], v[106:107], v[104:105]
	s_nop 0
	v_add_f32_e32 v3, v6, v7
	v_cvt_pk_bf16_f32 v6, v108, v4
	v_cvt_pk_bf16_f32 v7, v89, v90
	v_cvt_pk_bf16_f32 v8, v91, v94
	v_cvt_pk_bf16_f32 v9, v95, v100
	v_cvt_pk_bf16_f32 v10, v97, v86
	v_cvt_pk_bf16_f32 v11, v85, v82
	v_cvt_pk_bf16_f32 v12, v12, v80
	v_cvt_pk_bf16_f32 v13, v13, v104
	v_cvt_pk_bf16_f32 v80, v109, v88
	v_cvt_pk_bf16_f32 v81, v110, v92
	v_cvt_pk_bf16_f32 v82, v93, v98
	v_cvt_pk_bf16_f32 v83, v99, v96
	v_cvt_pk_bf16_f32 v84, v101, v84
	v_cvt_pk_bf16_f32 v85, v87, v14
	v_cvt_pk_bf16_f32 v86, v15, v102
	v_cvt_pk_bf16_f32 v87, v103, v106
	ds_read_b64_tr_b16 v[88:89], v167 offset:18432
	ds_read_b64_tr_b16 v[90:91], v167 offset:20992
	ds_read_b64_tr_b16 v[92:93], v167 offset:18496
	ds_read_b64_tr_b16 v[94:95], v167 offset:21056
	ds_read_b64_tr_b16 v[96:97], v167 offset:18560
	ds_read_b64_tr_b16 v[98:99], v167 offset:21120
	ds_read_b64_tr_b16 v[100:101], v167 offset:18624
	ds_read_b64_tr_b16 v[102:103], v167 offset:21184
	ds_read_b64_tr_b16 v[104:105], v167 offset:23552
	ds_read_b64_tr_b16 v[106:107], v167 offset:26112
	ds_read_b64_tr_b16 v[108:109], v167 offset:23616
	ds_read_b64_tr_b16 v[110:111], v167 offset:26176
	ds_read_b64_tr_b16 v[206:207], v167 offset:23680
	ds_read_b64_tr_b16 v[208:209], v167 offset:26240
	ds_read_b64_tr_b16 v[210:211], v167 offset:23744
	ds_read_b64_tr_b16 v[212:213], v167 offset:26304
	s_waitcnt lgkmcnt(14)
	v_mfma_f32_32x32x16_bf16 v[64:79], v[88:91], v[6:9], v[64:79]
	s_waitcnt lgkmcnt(12)
	v_mfma_f32_32x32x16_bf16 v[48:63], v[92:95], v[6:9], v[48:63]
	s_waitcnt lgkmcnt(10)
	v_mfma_f32_32x32x16_bf16 v[32:47], v[96:99], v[6:9], v[32:47]
	s_waitcnt lgkmcnt(8)
	v_mfma_f32_32x32x16_bf16 v[16:31], v[100:103], v[6:9], v[16:31]
	ds_read_b64_tr_b16 v[6:7], v167 offset:28672
	ds_read_b64_tr_b16 v[88:89], v167 offset:28736
	ds_read_b64_tr_b16 v[92:93], v167 offset:28800
	ds_read_b64_tr_b16 v[96:97], v167 offset:28864
	ds_read_b64_tr_b16 v[8:9], v167 offset:31232
	ds_read_b64_tr_b16 v[90:91], v167 offset:31296
	ds_read_b64_tr_b16 v[94:95], v167 offset:31360
	ds_read_b64_tr_b16 v[98:99], v167 offset:31424
	s_waitcnt lgkmcnt(14)
	v_mfma_f32_32x32x16_bf16 v[64:79], v[104:107], v[10:13], v[64:79]
	s_waitcnt lgkmcnt(12)
	v_mfma_f32_32x32x16_bf16 v[48:63], v[108:111], v[10:13], v[48:63]
	s_waitcnt lgkmcnt(10)
	v_mfma_f32_32x32x16_bf16 v[32:47], v[206:209], v[10:13], v[32:47]
	s_waitcnt lgkmcnt(8)
	v_mfma_f32_32x32x16_bf16 v[16:31], v[210:213], v[10:13], v[16:31]
	ds_read_b64_tr_b16 v[10:11], v167 offset:33792
	ds_read_b64_tr_b16 v[100:101], v167 offset:33856
	ds_read_b64_tr_b16 v[104:105], v167 offset:33920
	ds_read_b64_tr_b16 v[108:109], v167 offset:33984
	ds_read_b64_tr_b16 v[12:13], v167 offset:36352
	ds_read_b64_tr_b16 v[102:103], v167 offset:36416
	ds_read_b64_tr_b16 v[106:107], v167 offset:36480
	ds_read_b64_tr_b16 v[110:111], v167 offset:36544
	s_waitcnt lgkmcnt(11)
	v_mfma_f32_32x32x16_bf16 v[64:79], v[6:9], v[80:83], v[64:79]
	s_waitcnt lgkmcnt(10)
	v_mfma_f32_32x32x16_bf16 v[48:63], v[88:91], v[80:83], v[48:63]
	s_waitcnt lgkmcnt(9)
	v_mfma_f32_32x32x16_bf16 v[32:47], v[92:95], v[80:83], v[32:47]
	s_waitcnt lgkmcnt(8)
	v_mfma_f32_32x32x16_bf16 v[16:31], v[96:99], v[80:83], v[16:31]
	s_waitcnt lgkmcnt(3)
	v_mfma_f32_32x32x16_bf16 v[64:79], v[10:13], v[84:87], v[64:79]
	s_waitcnt lgkmcnt(2)
	v_mfma_f32_32x32x16_bf16 v[48:63], v[100:103], v[84:87], v[48:63]
	s_waitcnt lgkmcnt(1)
	v_mfma_f32_32x32x16_bf16 v[32:47], v[104:107], v[84:87], v[32:47]
	s_waitcnt lgkmcnt(0)
	v_mfma_f32_32x32x16_bf16 v[16:31], v[108:111], v[84:87], v[16:31]
	v_add_f32_e32 v168, v168, v3
	s_cmp_lt_i32 s24, 1
	s_cbranch_scc0 .LBB0_659
	s_branch .LBB0_660

.LBB0_677:
	v_exp_f32_e32 v104, v210
	v_exp_f32_e32 v105, v211
	v_exp_f32_e32 v4, v4
	v_exp_f32_e32 v86, v209
	v_exp_f32_e32 v106, v208
	v_add_f32_e32 v87, v105, v104
	v_exp_f32_e32 v90, v206
	v_pk_add_f32 v[88:89], v[86:87], v[4:5]
	v_exp_f32_e32 v87, v207
	v_pk_add_f32 v[88:89], v[88:89], v[88:89] op_sel_hi:[0,1]
	v_exp_f32_e32 v88, v99
	v_exp_f32_e32 v94, v97
	v_add_f32_e32 v91, v106, v87
	v_exp_f32_e32 v102, v1
	v_pk_add_f32 v[92:93], v[90:91], v[88:89]
	v_exp_f32_e32 v89, v98
	v_pk_add_f32 v[92:93], v[92:93], v[92:93] op_sel_hi:[0,1]
	v_exp_f32_e32 v91, v100
	v_exp_f32_e32 v92, v96
	v_exp_f32_e32 v100, v7
	v_add_f32_e32 v95, v91, v89
	v_pk_add_f32 v[96:97], v[94:95], v[92:93]
	v_exp_f32_e32 v93, v84
	v_pk_add_f32 v[96:97], v[96:97], v[96:97] op_sel_hi:[0,1]
	v_exp_f32_e32 v95, v85
	v_exp_f32_e32 v96, v81
	v_exp_f32_e32 v84, v83
	v_add_f32_e32 v85, v95, v93
	v_pk_add_f32 v[98:99], v[84:85], v[96:97]
	s_nop 0
	v_pk_add_f32 v[98:99], v[98:99], v[98:99] op_sel_hi:[0,1]
	v_exp_f32_e32 v85, v80
	v_exp_f32_e32 v97, v82
	v_exp_f32_e32 v98, v13
	v_exp_f32_e32 v80, v15
	v_add_f32_e32 v81, v97, v85
	v_pk_add_f32 v[82:83], v[80:81], v[98:99]
	s_nop 0
	v_pk_add_f32 v[82:83], v[82:83], v[82:83] op_sel_hi:[0,1]
	v_exp_f32_e32 v81, v12
	v_exp_f32_e32 v99, v14
	v_exp_f32_e32 v82, v9
	v_exp_f32_e32 v14, v11
	v_add_f32_e32 v15, v99, v81
	v_pk_add_f32 v[12:13], v[14:15], v[82:83]
	s_nop 0
	v_pk_add_f32 v[12:13], v[12:13], v[12:13] op_sel_hi:[0,1]
	v_exp_f32_e32 v15, v8
	v_exp_f32_e32 v83, v10
	v_exp_f32_e32 v12, v3
	v_add_f32_e32 v101, v83, v15
	v_pk_add_f32 v[8:9], v[100:101], v[12:13]
	v_exp_f32_e32 v101, v6
	v_pk_add_f32 v[10:11], v[8:9], v[8:9] op_sel_hi:[0,1]
	v_exp_f32_e32 v9, v2
	v_exp_f32_e32 v10, v0
	v_add_f32_e32 v103, v101, v9
	v_pk_add_f32 v[0:1], v[102:103], v[10:11]
	s_nop 0
	v_add_f32_e32 v210, v0, v1
	v_cvt_pk_bf16_f32 v0, v104, v4
	v_cvt_pk_bf16_f32 v1, v87, v88
	v_cvt_pk_bf16_f32 v2, v89, v92
	v_cvt_pk_bf16_f32 v3, v93, v96
	v_cvt_pk_bf16_f32 v6, v85, v98
	v_cvt_pk_bf16_f32 v7, v81, v82
	v_cvt_pk_bf16_f32 v8, v15, v12
	v_cvt_pk_bf16_f32 v9, v9, v10
	v_cvt_pk_bf16_f32 v10, v105, v86
	v_cvt_pk_bf16_f32 v11, v106, v90
	v_cvt_pk_bf16_f32 v12, v91, v94
	v_cvt_pk_bf16_f32 v13, v95, v84
	v_cvt_pk_bf16_f32 v80, v97, v80
	v_cvt_pk_bf16_f32 v81, v99, v14
	v_cvt_pk_bf16_f32 v82, v83, v100
	v_cvt_pk_bf16_f32 v83, v101, v102
	ds_read_b64_tr_b16 v[84:85], v167 offset:38912
	ds_read_b64_tr_b16 v[86:87], v167 offset:41472
	ds_read_b64_tr_b16 v[88:89], v167 offset:38976
	ds_read_b64_tr_b16 v[90:91], v167 offset:41536
	ds_read_b64_tr_b16 v[92:93], v167 offset:39040
	ds_read_b64_tr_b16 v[94:95], v167 offset:41600
	ds_read_b64_tr_b16 v[96:97], v167 offset:39104
	ds_read_b64_tr_b16 v[98:99], v167 offset:41664
	ds_read_b64_tr_b16 v[100:101], v167 offset:44032
	ds_read_b64_tr_b16 v[102:103], v167 offset:46592
	ds_read_b64_tr_b16 v[104:105], v167 offset:44096
	ds_read_b64_tr_b16 v[106:107], v167 offset:46656
	ds_read_b64_tr_b16 v[108:109], v167 offset:44160
	ds_read_b64_tr_b16 v[110:111], v167 offset:46720
	ds_read_b64_tr_b16 v[206:207], v167 offset:44224
	ds_read_b64_tr_b16 v[208:209], v167 offset:46784
	s_waitcnt lgkmcnt(14)
	v_mfma_f32_32x32x16_bf16 v[64:79], v[84:87], v[0:3], v[64:79]
	s_waitcnt lgkmcnt(12)
	v_mfma_f32_32x32x16_bf16 v[48:63], v[88:91], v[0:3], v[48:63]
	s_waitcnt lgkmcnt(10)
	v_mfma_f32_32x32x16_bf16 v[32:47], v[92:95], v[0:3], v[32:47]
	s_waitcnt lgkmcnt(8)
	v_mfma_f32_32x32x16_bf16 v[16:31], v[96:99], v[0:3], v[16:31]
	ds_read_b64_tr_b16 v[0:1], v167 offset:49152
	ds_read_b64_tr_b16 v[84:85], v167 offset:49216
	ds_read_b64_tr_b16 v[88:89], v167 offset:49280
	ds_read_b64_tr_b16 v[92:93], v167 offset:49344
	ds_read_b64_tr_b16 v[2:3], v167 offset:51712
	ds_read_b64_tr_b16 v[86:87], v167 offset:51776
	ds_read_b64_tr_b16 v[90:91], v167 offset:51840
	ds_read_b64_tr_b16 v[94:95], v167 offset:51904
	s_waitcnt lgkmcnt(14)
	v_mfma_f32_32x32x16_bf16 v[64:79], v[100:103], v[6:9], v[64:79]
	s_waitcnt lgkmcnt(12)
	v_mfma_f32_32x32x16_bf16 v[48:63], v[104:107], v[6:9], v[48:63]
	s_waitcnt lgkmcnt(10)
	v_mfma_f32_32x32x16_bf16 v[32:47], v[108:111], v[6:9], v[32:47]
	s_waitcnt lgkmcnt(8)
	v_mfma_f32_32x32x16_bf16 v[16:31], v[206:209], v[6:9], v[16:31]
	ds_read_b64_tr_b16 v[6:7], v167 offset:54272
	ds_read_b64_tr_b16 v[96:97], v167 offset:54336
	ds_read_b64_tr_b16 v[100:101], v167 offset:54400
	ds_read_b64_tr_b16 v[104:105], v167 offset:54464
	ds_read_b64_tr_b16 v[8:9], v167 offset:56832
	ds_read_b64_tr_b16 v[98:99], v167 offset:56896
	ds_read_b64_tr_b16 v[102:103], v167 offset:56960
	ds_read_b64_tr_b16 v[106:107], v167 offset:57024
	s_waitcnt lgkmcnt(11)
	v_mfma_f32_32x32x16_bf16 v[64:79], v[0:3], v[10:13], v[64:79]
	s_waitcnt lgkmcnt(10)
	v_mfma_f32_32x32x16_bf16 v[48:63], v[84:87], v[10:13], v[48:63]
	s_waitcnt lgkmcnt(9)
	v_mfma_f32_32x32x16_bf16 v[32:47], v[88:91], v[10:13], v[32:47]
	s_waitcnt lgkmcnt(8)
	v_mfma_f32_32x32x16_bf16 v[16:31], v[92:95], v[10:13], v[16:31]
	s_waitcnt lgkmcnt(3)
	v_mfma_f32_32x32x16_bf16 v[64:79], v[6:9], v[80:83], v[64:79]
	s_waitcnt lgkmcnt(2)
	v_mfma_f32_32x32x16_bf16 v[48:63], v[96:99], v[80:83], v[48:63]
	s_waitcnt lgkmcnt(1)
	v_mfma_f32_32x32x16_bf16 v[32:47], v[100:103], v[80:83], v[32:47]
	s_waitcnt lgkmcnt(0)
	v_mfma_f32_32x32x16_bf16 v[16:31], v[104:107], v[80:83], v[16:31]
	v_add_f32_e32 v168, v168, v210
	s_andn2_b64 vcc, exec, s[16:17]
	s_cbranch_vccz .LBB0_663
	s_branch .LBB0_664

.LBB0_699:
	v_exp_f32_e32 v170, v80
	v_exp_f32_e32 v171, v96
	v_exp_f32_e32 v10, v81
	v_exp_f32_e32 v4, v97
	v_exp_f32_e32 v172, v98
	v_add_f32_e32 v11, v170, v171
	v_pk_add_f32 v[12:13], v[10:11], v[4:5]
	s_nop 0
	v_pk_add_f32 v[14:15], v[12:13], v[12:13] op_sel_hi:[0,1]
	v_exp_f32_e32 v11, v82
	v_exp_f32_e32 v12, v83
	v_exp_f32_e32 v14, v99
	v_cvt_pk_bf16_f32 v10, v170, v10
	v_add_f32_e32 v13, v11, v172
	v_cvt_pk_bf16_f32 v11, v11, v12
	v_pk_add_f32 v[80:81], v[12:13], v[14:15]
	v_exp_f32_e32 v13, v84
	v_pk_add_f32 v[96:97], v[80:81], v[80:81] op_sel_hi:[0,1]
	v_exp_f32_e32 v15, v100
	v_exp_f32_e32 v80, v85
	v_exp_f32_e32 v96, v101
	v_cvt_pk_bf16_f32 v12, v13, v80
	v_add_f32_e32 v81, v13, v15
	v_pk_add_f32 v[82:83], v[80:81], v[96:97]
	s_nop 0
	v_pk_add_f32 v[98:99], v[82:83], v[82:83] op_sel_hi:[0,1]
	v_exp_f32_e32 v81, v86
	v_exp_f32_e32 v97, v102
	v_exp_f32_e32 v82, v87
	v_exp_f32_e32 v98, v103
	v_cvt_pk_bf16_f32 v13, v81, v82
	v_add_f32_e32 v83, v81, v97
	v_pk_add_f32 v[84:85], v[82:83], v[98:99]
	s_nop 0
	v_pk_add_f32 v[100:101], v[84:85], v[84:85] op_sel_hi:[0,1]
	v_exp_f32_e32 v83, v88
	v_exp_f32_e32 v99, v104
	v_exp_f32_e32 v84, v89
	v_exp_f32_e32 v100, v105
	v_exp_f32_e32 v104, v95
	v_add_f32_e32 v85, v83, v99
	v_cvt_pk_bf16_f32 v80, v83, v84
	v_pk_add_f32 v[86:87], v[84:85], v[100:101]
	v_exp_f32_e32 v85, v90
	v_pk_add_f32 v[102:103], v[86:87], v[86:87] op_sel_hi:[0,1]
	v_exp_f32_e32 v101, v106
	v_exp_f32_e32 v86, v91
	v_exp_f32_e32 v102, v107
	v_cvt_pk_bf16_f32 v81, v85, v86
	v_add_f32_e32 v87, v85, v101
	v_pk_add_f32 v[88:89], v[86:87], v[102:103]
	s_nop 0
	v_pk_add_f32 v[90:91], v[88:89], v[88:89] op_sel_hi:[0,1]
	v_exp_f32_e32 v87, v92
	v_exp_f32_e32 v103, v108
	v_exp_f32_e32 v88, v93
	v_exp_f32_e32 v90, v109
	v_cvt_pk_bf16_f32 v82, v87, v88
	v_add_f32_e32 v89, v87, v103
	v_pk_add_f32 v[92:93], v[88:89], v[90:91]
	s_nop 0
	v_pk_add_f32 v[92:93], v[92:93], v[92:93] op_sel_hi:[0,1]
	v_exp_f32_e32 v89, v94
	v_exp_f32_e32 v91, v110
	v_exp_f32_e32 v92, v111
	v_cvt_pk_bf16_f32 v83, v89, v104
	v_cvt_pk_bf16_f32 v84, v171, v4
	v_add_f32_e32 v105, v89, v91
	v_pk_add_f32 v[94:95], v[104:105], v[92:93]
	v_add_u32_e32 v4, s61, v167
	v_add_f32_e32 v180, v94, v95
	v_cvt_pk_bf16_f32 v85, v172, v14
	v_cvt_pk_bf16_f32 v86, v15, v96
	v_cvt_pk_bf16_f32 v87, v97, v98
	v_cvt_pk_bf16_f32 v88, v99, v100
	v_cvt_pk_bf16_f32 v89, v101, v102
	v_cvt_pk_bf16_f32 v90, v103, v90
	v_cvt_pk_bf16_f32 v91, v91, v92
	ds_read_b64_tr_b16 v[92:93], v4 offset:18432
	ds_read_b64_tr_b16 v[94:95], v4 offset:20992
	ds_read_b64_tr_b16 v[96:97], v4 offset:18496
	ds_read_b64_tr_b16 v[98:99], v4 offset:21056
	ds_read_b64_tr_b16 v[100:101], v4 offset:18560
	ds_read_b64_tr_b16 v[102:103], v4 offset:21120
	ds_read_b64_tr_b16 v[104:105], v4 offset:18624
	ds_read_b64_tr_b16 v[106:107], v4 offset:21184
	ds_read_b64_tr_b16 v[108:109], v4 offset:23552
	ds_read_b64_tr_b16 v[110:111], v4 offset:26112
	ds_read_b64_tr_b16 v[170:171], v4 offset:23616
	ds_read_b64_tr_b16 v[172:173], v4 offset:26176
	ds_read_b64_tr_b16 v[176:177], v4 offset:23680
	ds_read_b64_tr_b16 v[178:179], v4 offset:26240
	ds_read_b64_tr_b16 v[204:205], v4 offset:23744
	ds_read_b64_tr_b16 v[206:207], v4 offset:26304
	s_waitcnt lgkmcnt(14)
	v_mfma_f32_32x32x16_bf16 v[64:79], v[92:95], v[10:13], v[64:79]
	s_waitcnt lgkmcnt(12)
	v_mfma_f32_32x32x16_bf16 v[48:63], v[96:99], v[10:13], v[48:63]
	s_waitcnt lgkmcnt(10)
	v_mfma_f32_32x32x16_bf16 v[32:47], v[100:103], v[10:13], v[32:47]
	s_waitcnt lgkmcnt(8)
	v_mfma_f32_32x32x16_bf16 v[16:31], v[104:107], v[10:13], v[16:31]
	ds_read_b64_tr_b16 v[10:11], v4 offset:28672
	ds_read_b64_tr_b16 v[92:93], v4 offset:28736
	ds_read_b64_tr_b16 v[96:97], v4 offset:28800
	ds_read_b64_tr_b16 v[100:101], v4 offset:28864
	ds_read_b64_tr_b16 v[12:13], v4 offset:31232
	ds_read_b64_tr_b16 v[94:95], v4 offset:31296
	ds_read_b64_tr_b16 v[98:99], v4 offset:31360
	ds_read_b64_tr_b16 v[102:103], v4 offset:31424
	s_waitcnt lgkmcnt(14)
	v_mfma_f32_32x32x16_bf16 v[64:79], v[108:111], v[80:83], v[64:79]
	s_waitcnt lgkmcnt(12)
	v_mfma_f32_32x32x16_bf16 v[48:63], v[170:173], v[80:83], v[48:63]
	s_waitcnt lgkmcnt(10)
	v_mfma_f32_32x32x16_bf16 v[32:47], v[176:179], v[80:83], v[32:47]
	s_waitcnt lgkmcnt(8)
	v_mfma_f32_32x32x16_bf16 v[16:31], v[204:207], v[80:83], v[16:31]
	ds_read_b64_tr_b16 v[80:81], v4 offset:33792
	ds_read_b64_tr_b16 v[104:105], v4 offset:33856
	ds_read_b64_tr_b16 v[108:109], v4 offset:33920
	ds_read_b64_tr_b16 v[170:171], v4 offset:33984
	ds_read_b64_tr_b16 v[82:83], v4 offset:36352
	ds_read_b64_tr_b16 v[106:107], v4 offset:36416
	ds_read_b64_tr_b16 v[110:111], v4 offset:36480
	ds_read_b64_tr_b16 v[172:173], v4 offset:36544
	s_waitcnt lgkmcnt(11)
	v_mfma_f32_32x32x16_bf16 v[64:79], v[10:13], v[84:87], v[64:79]
	s_waitcnt lgkmcnt(10)
	v_mfma_f32_32x32x16_bf16 v[48:63], v[92:95], v[84:87], v[48:63]
	s_waitcnt lgkmcnt(9)
	v_mfma_f32_32x32x16_bf16 v[32:47], v[96:99], v[84:87], v[32:47]
	s_waitcnt lgkmcnt(8)
	v_mfma_f32_32x32x16_bf16 v[16:31], v[100:103], v[84:87], v[16:31]
	s_waitcnt lgkmcnt(3)
	v_mfma_f32_32x32x16_bf16 v[64:79], v[80:83], v[88:91], v[64:79]
	s_waitcnt lgkmcnt(2)
	v_mfma_f32_32x32x16_bf16 v[48:63], v[104:107], v[88:91], v[48:63]
	s_waitcnt lgkmcnt(1)
	v_mfma_f32_32x32x16_bf16 v[32:47], v[108:111], v[88:91], v[32:47]
	s_waitcnt lgkmcnt(0)
	v_mfma_f32_32x32x16_bf16 v[16:31], v[170:173], v[88:91], v[16:31]
	v_add_f32_e32 v168, v168, v180
	s_cmp_eq_u32 s52, 0
	s_cbranch_scc0 .LBB0_685
	s_branch .LBB0_686

.LBB0_704:
	v_exp_f32_e32 v7, v80
	v_exp_f32_e32 v170, v96
	v_exp_f32_e32 v8, v81
	v_exp_f32_e32 v4, v97
	v_exp_f32_e32 v171, v98
	v_add_f32_e32 v9, v7, v170
	v_exp_f32_e32 v98, v91
	v_pk_add_f32 v[10:11], v[8:9], v[4:5]
	v_exp_f32_e32 v9, v82
	v_pk_add_f32 v[96:97], v[10:11], v[10:11] op_sel_hi:[0,1]
	v_exp_f32_e32 v10, v83
	v_exp_f32_e32 v96, v99
	v_add_f32_e32 v11, v9, v171
	v_cvt_pk_bf16_f32 v8, v7, v8
	v_cvt_pk_bf16_f32 v9, v9, v10
	v_pk_add_f32 v[12:13], v[10:11], v[96:97]
	v_exp_f32_e32 v11, v84
	v_pk_add_f32 v[82:83], v[12:13], v[12:13] op_sel_hi:[0,1]
	v_exp_f32_e32 v97, v100
	v_exp_f32_e32 v12, v85
	v_exp_f32_e32 v82, v101
	v_exp_f32_e32 v100, v93
	v_add_f32_e32 v13, v11, v97
	v_cvt_pk_bf16_f32 v10, v11, v12
	v_pk_add_f32 v[14:15], v[12:13], v[82:83]
	v_exp_f32_e32 v13, v86
	v_pk_add_f32 v[84:85], v[14:15], v[14:15] op_sel_hi:[0,1]
	v_exp_f32_e32 v83, v102
	v_exp_f32_e32 v14, v87
	v_exp_f32_e32 v84, v103
	v_exp_f32_e32 v102, v95
	v_add_f32_e32 v15, v13, v83
	v_cvt_pk_bf16_f32 v11, v13, v14
	v_pk_add_f32 v[80:81], v[14:15], v[84:85]
	v_exp_f32_e32 v15, v88
	v_pk_add_f32 v[86:87], v[80:81], v[80:81] op_sel_hi:[0,1]
	v_exp_f32_e32 v85, v104
	v_exp_f32_e32 v80, v89
	v_exp_f32_e32 v86, v105
	v_cvt_pk_bf16_f32 v12, v15, v80
	v_add_f32_e32 v81, v15, v85
	v_pk_add_f32 v[88:89], v[80:81], v[86:87]
	s_nop 0
	v_pk_add_f32 v[88:89], v[88:89], v[88:89] op_sel_hi:[0,1]
	v_exp_f32_e32 v81, v90
	v_exp_f32_e32 v87, v106
	v_exp_f32_e32 v88, v107
	v_cvt_pk_bf16_f32 v13, v81, v98
	v_add_f32_e32 v99, v81, v87
	v_pk_add_f32 v[90:91], v[98:99], v[88:89]
	v_exp_f32_e32 v89, v92
	v_pk_add_f32 v[90:91], v[90:91], v[90:91] op_sel_hi:[0,1]
	v_exp_f32_e32 v99, v108
	v_exp_f32_e32 v90, v109
	v_cvt_pk_bf16_f32 v14, v89, v100
	v_add_f32_e32 v101, v89, v99
	v_pk_add_f32 v[92:93], v[100:101], v[90:91]
	v_exp_f32_e32 v91, v94
	v_pk_add_f32 v[92:93], v[92:93], v[92:93] op_sel_hi:[0,1]
	v_exp_f32_e32 v101, v110
	v_exp_f32_e32 v92, v111
	v_cvt_pk_bf16_f32 v15, v91, v102
	v_cvt_pk_bf16_f32 v80, v170, v4
	v_add_f32_e32 v103, v91, v101
	v_pk_add_f32 v[94:95], v[102:103], v[92:93]
	v_add_u32_e32 v4, s63, v167
	v_add_f32_e32 v180, v94, v95
	v_cvt_pk_bf16_f32 v81, v171, v96
	v_cvt_pk_bf16_f32 v82, v97, v82
	v_cvt_pk_bf16_f32 v83, v83, v84
	v_cvt_pk_bf16_f32 v84, v85, v86
	v_cvt_pk_bf16_f32 v85, v87, v88
	v_cvt_pk_bf16_f32 v86, v99, v90
	v_cvt_pk_bf16_f32 v87, v101, v92
	ds_read_b64_tr_b16 v[88:89], v4 offset:18432
	ds_read_b64_tr_b16 v[90:91], v4 offset:20992
	ds_read_b64_tr_b16 v[92:93], v4 offset:18496
	ds_read_b64_tr_b16 v[94:95], v4 offset:21056
	ds_read_b64_tr_b16 v[96:97], v4 offset:18560
	ds_read_b64_tr_b16 v[98:99], v4 offset:21120
	ds_read_b64_tr_b16 v[100:101], v4 offset:18624
	ds_read_b64_tr_b16 v[102:103], v4 offset:21184
	ds_read_b64_tr_b16 v[104:105], v4 offset:23552
	ds_read_b64_tr_b16 v[106:107], v4 offset:26112
	ds_read_b64_tr_b16 v[108:109], v4 offset:23616
	ds_read_b64_tr_b16 v[110:111], v4 offset:26176
	ds_read_b64_tr_b16 v[170:171], v4 offset:23680
	ds_read_b64_tr_b16 v[172:173], v4 offset:26240
	ds_read_b64_tr_b16 v[176:177], v4 offset:23744
	ds_read_b64_tr_b16 v[178:179], v4 offset:26304
	s_waitcnt lgkmcnt(14)
	v_mfma_f32_32x32x16_bf16 v[64:79], v[88:91], v[8:11], v[64:79]
	s_waitcnt lgkmcnt(12)
	v_mfma_f32_32x32x16_bf16 v[48:63], v[92:95], v[8:11], v[48:63]
	s_waitcnt lgkmcnt(10)
	v_mfma_f32_32x32x16_bf16 v[32:47], v[96:99], v[8:11], v[32:47]
	s_waitcnt lgkmcnt(8)
	v_mfma_f32_32x32x16_bf16 v[16:31], v[100:103], v[8:11], v[16:31]
	ds_read_b64_tr_b16 v[8:9], v4 offset:28672
	ds_read_b64_tr_b16 v[88:89], v4 offset:28736
	ds_read_b64_tr_b16 v[92:93], v4 offset:28800
	ds_read_b64_tr_b16 v[96:97], v4 offset:28864
	ds_read_b64_tr_b16 v[10:11], v4 offset:31232
	ds_read_b64_tr_b16 v[90:91], v4 offset:31296
	ds_read_b64_tr_b16 v[94:95], v4 offset:31360
	ds_read_b64_tr_b16 v[98:99], v4 offset:31424
	s_waitcnt lgkmcnt(14)
	v_mfma_f32_32x32x16_bf16 v[64:79], v[104:107], v[12:15], v[64:79]
	s_waitcnt lgkmcnt(12)
	v_mfma_f32_32x32x16_bf16 v[48:63], v[108:111], v[12:15], v[48:63]
	s_waitcnt lgkmcnt(10)
	v_mfma_f32_32x32x16_bf16 v[32:47], v[170:173], v[12:15], v[32:47]
	s_waitcnt lgkmcnt(8)
	v_mfma_f32_32x32x16_bf16 v[16:31], v[176:179], v[12:15], v[16:31]
	ds_read_b64_tr_b16 v[12:13], v4 offset:33792
	ds_read_b64_tr_b16 v[100:101], v4 offset:33856
	ds_read_b64_tr_b16 v[104:105], v4 offset:33920
	ds_read_b64_tr_b16 v[108:109], v4 offset:33984
	ds_read_b64_tr_b16 v[14:15], v4 offset:36352
	ds_read_b64_tr_b16 v[102:103], v4 offset:36416
	ds_read_b64_tr_b16 v[106:107], v4 offset:36480
	ds_read_b64_tr_b16 v[110:111], v4 offset:36544
	s_waitcnt lgkmcnt(11)
	v_mfma_f32_32x32x16_bf16 v[64:79], v[8:11], v[80:83], v[64:79]
	s_waitcnt lgkmcnt(10)
	v_mfma_f32_32x32x16_bf16 v[48:63], v[88:91], v[80:83], v[48:63]
	s_waitcnt lgkmcnt(9)
	v_mfma_f32_32x32x16_bf16 v[32:47], v[92:95], v[80:83], v[32:47]
	s_waitcnt lgkmcnt(8)
	v_mfma_f32_32x32x16_bf16 v[16:31], v[96:99], v[80:83], v[16:31]
	s_waitcnt lgkmcnt(3)
	v_mfma_f32_32x32x16_bf16 v[64:79], v[12:15], v[84:87], v[64:79]
	s_waitcnt lgkmcnt(2)
	v_mfma_f32_32x32x16_bf16 v[48:63], v[100:103], v[84:87], v[48:63]
	s_waitcnt lgkmcnt(1)
	v_mfma_f32_32x32x16_bf16 v[32:47], v[104:107], v[84:87], v[32:47]
	s_waitcnt lgkmcnt(0)
	v_mfma_f32_32x32x16_bf16 v[16:31], v[108:111], v[84:87], v[16:31]
	v_add_f32_e32 v168, v168, v180
	s_andn2_b64 vcc, exec, s[18:19]
	s_cbranch_vccnz .LBB0_681

.LBB0_724:
	v_exp_f32_e32 v108, v243
	v_exp_f32_e32 v109, v244
	v_exp_f32_e32 v4, v4
	v_exp_f32_e32 v88, v242
	v_exp_f32_e32 v110, v241
	v_add_f32_e32 v89, v109, v108
	v_exp_f32_e32 v92, v239
	v_pk_add_f32 v[90:91], v[88:89], v[4:5]
	v_exp_f32_e32 v89, v240
	v_pk_add_f32 v[90:91], v[90:91], v[90:91] op_sel_hi:[0,1]
	v_exp_f32_e32 v90, v238
	v_exp_f32_e32 v98, v98
	v_add_f32_e32 v93, v110, v89
	v_exp_f32_e32 v14, v14
	v_pk_add_f32 v[94:95], v[92:93], v[90:91]
	v_exp_f32_e32 v91, v99
	v_pk_add_f32 v[94:95], v[94:95], v[94:95] op_sel_hi:[0,1]
	v_exp_f32_e32 v93, v100
	v_exp_f32_e32 v94, v97
	v_exp_f32_e32 v102, v10
	v_exp_f32_e32 v106, v6
	v_add_f32_e32 v99, v93, v91
	v_pk_add_f32 v[100:101], v[98:99], v[94:95]
	v_exp_f32_e32 v95, v96
	v_pk_add_f32 v[100:101], v[100:101], v[100:101] op_sel_hi:[0,1]
	v_exp_f32_e32 v99, v86
	v_exp_f32_e32 v100, v84
	v_exp_f32_e32 v96, v87
	v_exp_f32_e32 v84, v82
	v_add_f32_e32 v97, v99, v95
	v_pk_add_f32 v[86:87], v[96:97], v[100:101]
	s_nop 0
	v_pk_add_f32 v[86:87], v[86:87], v[86:87] op_sel_hi:[0,1]
	v_exp_f32_e32 v97, v83
	v_exp_f32_e32 v101, v85
	v_exp_f32_e32 v86, v80
	v_add_f32_e32 v85, v101, v97
	v_pk_add_f32 v[82:83], v[84:85], v[86:87]
	v_exp_f32_e32 v85, v15
	v_pk_add_f32 v[82:83], v[82:83], v[82:83] op_sel_hi:[0,1]
	v_exp_f32_e32 v87, v81
	v_exp_f32_e32 v82, v12
	v_exp_f32_e32 v12, v11
	v_add_f32_e32 v15, v87, v85
	v_pk_add_f32 v[80:81], v[14:15], v[82:83]
	v_exp_f32_e32 v15, v13
	v_pk_add_f32 v[80:81], v[80:81], v[80:81] op_sel_hi:[0,1]
	v_exp_f32_e32 v80, v8
	v_exp_f32_e32 v13, v7
	v_add_f32_e32 v103, v15, v12
	v_pk_add_f32 v[10:11], v[102:103], v[80:81]
	s_nop 0
	v_pk_add_f32 v[104:105], v[10:11], v[10:11] op_sel_hi:[0,1]
	v_exp_f32_e32 v103, v9
	v_exp_f32_e32 v104, v3
	v_add_f32_e32 v107, v103, v13
	v_pk_add_f32 v[6:7], v[106:107], v[104:105]
	s_nop 0
	v_add_f32_e32 v3, v6, v7
	v_cvt_pk_bf16_f32 v6, v108, v4
	v_cvt_pk_bf16_f32 v7, v89, v90
	v_cvt_pk_bf16_f32 v8, v91, v94
	v_cvt_pk_bf16_f32 v9, v95, v100
	v_cvt_pk_bf16_f32 v10, v97, v86
	v_cvt_pk_bf16_f32 v11, v85, v82
	v_cvt_pk_bf16_f32 v12, v12, v80
	v_cvt_pk_bf16_f32 v13, v13, v104
	v_cvt_pk_bf16_f32 v80, v109, v88
	v_cvt_pk_bf16_f32 v81, v110, v92
	v_cvt_pk_bf16_f32 v82, v93, v98
	v_cvt_pk_bf16_f32 v83, v99, v96
	v_cvt_pk_bf16_f32 v84, v101, v84
	v_cvt_pk_bf16_f32 v85, v87, v14
	v_cvt_pk_bf16_f32 v86, v15, v102
	v_cvt_pk_bf16_f32 v87, v103, v106
	ds_read_b64_tr_b16 v[88:89], v223 offset:18432
	ds_read_b64_tr_b16 v[90:91], v223 offset:20992
	ds_read_b64_tr_b16 v[92:93], v223 offset:18496
	ds_read_b64_tr_b16 v[94:95], v223 offset:21056
	ds_read_b64_tr_b16 v[96:97], v223 offset:18560
	ds_read_b64_tr_b16 v[98:99], v223 offset:21120
	ds_read_b64_tr_b16 v[100:101], v223 offset:18624
	ds_read_b64_tr_b16 v[102:103], v223 offset:21184
	ds_read_b64_tr_b16 v[104:105], v223 offset:23552
	ds_read_b64_tr_b16 v[106:107], v223 offset:26112
	ds_read_b64_tr_b16 v[108:109], v223 offset:23616
	ds_read_b64_tr_b16 v[110:111], v223 offset:26176
	ds_read_b64_tr_b16 v[238:239], v223 offset:23680
	ds_read_b64_tr_b16 v[240:241], v223 offset:26240
	ds_read_b64_tr_b16 v[242:243], v223 offset:23744
	ds_read_b64_tr_b16 v[244:245], v223 offset:26304
	s_waitcnt lgkmcnt(14)
	v_mfma_f32_32x32x16_bf16 v[64:79], v[88:91], v[6:9], v[64:79]
	s_waitcnt lgkmcnt(12)
	v_mfma_f32_32x32x16_bf16 v[48:63], v[92:95], v[6:9], v[48:63]
	s_waitcnt lgkmcnt(10)
	v_mfma_f32_32x32x16_bf16 v[32:47], v[96:99], v[6:9], v[32:47]
	s_waitcnt lgkmcnt(8)
	v_mfma_f32_32x32x16_bf16 v[16:31], v[100:103], v[6:9], v[16:31]
	ds_read_b64_tr_b16 v[6:7], v223 offset:28672
	ds_read_b64_tr_b16 v[88:89], v223 offset:28736
	ds_read_b64_tr_b16 v[92:93], v223 offset:28800
	ds_read_b64_tr_b16 v[96:97], v223 offset:28864
	ds_read_b64_tr_b16 v[8:9], v223 offset:31232
	ds_read_b64_tr_b16 v[90:91], v223 offset:31296
	ds_read_b64_tr_b16 v[94:95], v223 offset:31360
	ds_read_b64_tr_b16 v[98:99], v223 offset:31424
	s_waitcnt lgkmcnt(14)
	v_mfma_f32_32x32x16_bf16 v[64:79], v[104:107], v[10:13], v[64:79]
	s_waitcnt lgkmcnt(12)
	v_mfma_f32_32x32x16_bf16 v[48:63], v[108:111], v[10:13], v[48:63]
	s_waitcnt lgkmcnt(10)
	v_mfma_f32_32x32x16_bf16 v[32:47], v[238:241], v[10:13], v[32:47]
	s_waitcnt lgkmcnt(8)
	v_mfma_f32_32x32x16_bf16 v[16:31], v[242:245], v[10:13], v[16:31]
	ds_read_b64_tr_b16 v[10:11], v223 offset:33792
	ds_read_b64_tr_b16 v[100:101], v223 offset:33856
	ds_read_b64_tr_b16 v[104:105], v223 offset:33920
	ds_read_b64_tr_b16 v[108:109], v223 offset:33984
	ds_read_b64_tr_b16 v[12:13], v223 offset:36352
	ds_read_b64_tr_b16 v[102:103], v223 offset:36416
	ds_read_b64_tr_b16 v[106:107], v223 offset:36480
	ds_read_b64_tr_b16 v[110:111], v223 offset:36544
	s_waitcnt lgkmcnt(11)
	v_mfma_f32_32x32x16_bf16 v[64:79], v[6:9], v[80:83], v[64:79]
	s_waitcnt lgkmcnt(10)
	v_mfma_f32_32x32x16_bf16 v[48:63], v[88:91], v[80:83], v[48:63]
	s_waitcnt lgkmcnt(9)
	v_mfma_f32_32x32x16_bf16 v[32:47], v[92:95], v[80:83], v[32:47]
	s_waitcnt lgkmcnt(8)
	v_mfma_f32_32x32x16_bf16 v[16:31], v[96:99], v[80:83], v[16:31]
	s_waitcnt lgkmcnt(3)
	v_mfma_f32_32x32x16_bf16 v[64:79], v[10:13], v[84:87], v[64:79]
	s_waitcnt lgkmcnt(2)
	v_mfma_f32_32x32x16_bf16 v[48:63], v[100:103], v[84:87], v[48:63]
	s_waitcnt lgkmcnt(1)
	v_mfma_f32_32x32x16_bf16 v[32:47], v[104:107], v[84:87], v[32:47]
	s_waitcnt lgkmcnt(0)
	v_mfma_f32_32x32x16_bf16 v[16:31], v[108:111], v[84:87], v[16:31]
	v_add_f32_e32 v224, v224, v3
	s_cmp_lt_i32 s21, 1
	s_cbranch_scc0 .LBB0_712
	s_branch .LBB0_713

.LBB0_730:
	v_exp_f32_e32 v104, v242
	v_exp_f32_e32 v105, v243
	v_exp_f32_e32 v4, v4
	v_exp_f32_e32 v86, v241
	v_exp_f32_e32 v106, v240
	v_add_f32_e32 v87, v105, v104
	v_exp_f32_e32 v90, v238
	v_pk_add_f32 v[88:89], v[86:87], v[4:5]
	v_exp_f32_e32 v87, v239
	v_pk_add_f32 v[88:89], v[88:89], v[88:89] op_sel_hi:[0,1]
	v_exp_f32_e32 v88, v99
	v_exp_f32_e32 v94, v97
	v_add_f32_e32 v91, v106, v87
	v_exp_f32_e32 v102, v1
	v_pk_add_f32 v[92:93], v[90:91], v[88:89]
	v_exp_f32_e32 v89, v98
	v_pk_add_f32 v[92:93], v[92:93], v[92:93] op_sel_hi:[0,1]
	v_exp_f32_e32 v91, v100
	v_exp_f32_e32 v92, v96
	v_exp_f32_e32 v100, v7
	v_add_f32_e32 v95, v91, v89
	v_pk_add_f32 v[96:97], v[94:95], v[92:93]
	v_exp_f32_e32 v93, v84
	v_pk_add_f32 v[96:97], v[96:97], v[96:97] op_sel_hi:[0,1]
	v_exp_f32_e32 v95, v85
	v_exp_f32_e32 v96, v81
	v_exp_f32_e32 v84, v83
	v_add_f32_e32 v85, v95, v93
	v_pk_add_f32 v[98:99], v[84:85], v[96:97]
	s_nop 0
	v_pk_add_f32 v[98:99], v[98:99], v[98:99] op_sel_hi:[0,1]
	v_exp_f32_e32 v85, v80
	v_exp_f32_e32 v97, v82
	v_exp_f32_e32 v98, v13
	v_exp_f32_e32 v80, v15
	v_add_f32_e32 v81, v97, v85
	v_pk_add_f32 v[82:83], v[80:81], v[98:99]
	s_nop 0
	v_pk_add_f32 v[82:83], v[82:83], v[82:83] op_sel_hi:[0,1]
	v_exp_f32_e32 v81, v12
	v_exp_f32_e32 v99, v14
	v_exp_f32_e32 v82, v9
	v_exp_f32_e32 v14, v11
	v_add_f32_e32 v15, v99, v81
	v_pk_add_f32 v[12:13], v[14:15], v[82:83]
	s_nop 0
	v_pk_add_f32 v[12:13], v[12:13], v[12:13] op_sel_hi:[0,1]
	v_exp_f32_e32 v15, v8
	v_exp_f32_e32 v83, v10
	v_exp_f32_e32 v12, v3
	v_add_f32_e32 v101, v83, v15
	v_pk_add_f32 v[8:9], v[100:101], v[12:13]
	v_exp_f32_e32 v101, v6
	v_pk_add_f32 v[10:11], v[8:9], v[8:9] op_sel_hi:[0,1]
	v_exp_f32_e32 v9, v2
	v_exp_f32_e32 v10, v0
	v_add_f32_e32 v103, v101, v9
	v_pk_add_f32 v[0:1], v[102:103], v[10:11]
	s_nop 0
	v_add_f32_e32 v242, v0, v1
	v_cvt_pk_bf16_f32 v0, v104, v4
	v_cvt_pk_bf16_f32 v1, v87, v88
	v_cvt_pk_bf16_f32 v2, v89, v92
	v_cvt_pk_bf16_f32 v3, v93, v96
	v_cvt_pk_bf16_f32 v6, v85, v98
	v_cvt_pk_bf16_f32 v7, v81, v82
	v_cvt_pk_bf16_f32 v8, v15, v12
	v_cvt_pk_bf16_f32 v9, v9, v10
	v_cvt_pk_bf16_f32 v10, v105, v86
	v_cvt_pk_bf16_f32 v11, v106, v90
	v_cvt_pk_bf16_f32 v12, v91, v94
	v_cvt_pk_bf16_f32 v13, v95, v84
	v_cvt_pk_bf16_f32 v80, v97, v80
	v_cvt_pk_bf16_f32 v81, v99, v14
	v_cvt_pk_bf16_f32 v82, v83, v100
	v_cvt_pk_bf16_f32 v83, v101, v102
	ds_read_b64_tr_b16 v[84:85], v223 offset:38912
	ds_read_b64_tr_b16 v[86:87], v223 offset:41472
	ds_read_b64_tr_b16 v[88:89], v223 offset:38976
	ds_read_b64_tr_b16 v[90:91], v223 offset:41536
	ds_read_b64_tr_b16 v[92:93], v223 offset:39040
	ds_read_b64_tr_b16 v[94:95], v223 offset:41600
	ds_read_b64_tr_b16 v[96:97], v223 offset:39104
	ds_read_b64_tr_b16 v[98:99], v223 offset:41664
	ds_read_b64_tr_b16 v[100:101], v223 offset:44032
	ds_read_b64_tr_b16 v[102:103], v223 offset:46592
	ds_read_b64_tr_b16 v[104:105], v223 offset:44096
	ds_read_b64_tr_b16 v[106:107], v223 offset:46656
	ds_read_b64_tr_b16 v[108:109], v223 offset:44160
	ds_read_b64_tr_b16 v[110:111], v223 offset:46720
	ds_read_b64_tr_b16 v[238:239], v223 offset:44224
	ds_read_b64_tr_b16 v[240:241], v223 offset:46784
	s_waitcnt lgkmcnt(14)
	v_mfma_f32_32x32x16_bf16 v[64:79], v[84:87], v[0:3], v[64:79]
	s_waitcnt lgkmcnt(12)
	v_mfma_f32_32x32x16_bf16 v[48:63], v[88:91], v[0:3], v[48:63]
	s_waitcnt lgkmcnt(10)
	v_mfma_f32_32x32x16_bf16 v[32:47], v[92:95], v[0:3], v[32:47]
	s_waitcnt lgkmcnt(8)
	v_mfma_f32_32x32x16_bf16 v[16:31], v[96:99], v[0:3], v[16:31]
	ds_read_b64_tr_b16 v[0:1], v223 offset:49152
	ds_read_b64_tr_b16 v[84:85], v223 offset:49216
	ds_read_b64_tr_b16 v[88:89], v223 offset:49280
	ds_read_b64_tr_b16 v[92:93], v223 offset:49344
	ds_read_b64_tr_b16 v[2:3], v223 offset:51712
	ds_read_b64_tr_b16 v[86:87], v223 offset:51776
	ds_read_b64_tr_b16 v[90:91], v223 offset:51840
	ds_read_b64_tr_b16 v[94:95], v223 offset:51904
	s_waitcnt lgkmcnt(14)
	v_mfma_f32_32x32x16_bf16 v[64:79], v[100:103], v[6:9], v[64:79]
	s_waitcnt lgkmcnt(12)
	v_mfma_f32_32x32x16_bf16 v[48:63], v[104:107], v[6:9], v[48:63]
	s_waitcnt lgkmcnt(10)
	v_mfma_f32_32x32x16_bf16 v[32:47], v[108:111], v[6:9], v[32:47]
	s_waitcnt lgkmcnt(8)
	v_mfma_f32_32x32x16_bf16 v[16:31], v[238:241], v[6:9], v[16:31]
	ds_read_b64_tr_b16 v[6:7], v223 offset:54272
	ds_read_b64_tr_b16 v[96:97], v223 offset:54336
	ds_read_b64_tr_b16 v[100:101], v223 offset:54400
	ds_read_b64_tr_b16 v[104:105], v223 offset:54464
	ds_read_b64_tr_b16 v[8:9], v223 offset:56832
	ds_read_b64_tr_b16 v[98:99], v223 offset:56896
	ds_read_b64_tr_b16 v[102:103], v223 offset:56960
	ds_read_b64_tr_b16 v[106:107], v223 offset:57024
	s_waitcnt lgkmcnt(11)
	v_mfma_f32_32x32x16_bf16 v[64:79], v[0:3], v[10:13], v[64:79]
	s_waitcnt lgkmcnt(10)
	v_mfma_f32_32x32x16_bf16 v[48:63], v[84:87], v[10:13], v[48:63]
	s_waitcnt lgkmcnt(9)
	v_mfma_f32_32x32x16_bf16 v[32:47], v[88:91], v[10:13], v[32:47]
	s_waitcnt lgkmcnt(8)
	v_mfma_f32_32x32x16_bf16 v[16:31], v[92:95], v[10:13], v[16:31]
	s_waitcnt lgkmcnt(3)
	v_mfma_f32_32x32x16_bf16 v[64:79], v[6:9], v[80:83], v[64:79]
	s_waitcnt lgkmcnt(2)
	v_mfma_f32_32x32x16_bf16 v[48:63], v[96:99], v[80:83], v[48:63]
	s_waitcnt lgkmcnt(1)
	v_mfma_f32_32x32x16_bf16 v[32:47], v[100:103], v[80:83], v[32:47]
	s_waitcnt lgkmcnt(0)
	v_mfma_f32_32x32x16_bf16 v[16:31], v[104:107], v[80:83], v[16:31]
	v_add_f32_e32 v224, v224, v242
	s_andn2_b64 vcc, exec, s[14:15]
	s_cbranch_vccz .LBB0_716
	s_branch .LBB0_717

.LBB0_752:
	v_exp_f32_e32 v226, v80
	v_exp_f32_e32 v227, v96
	v_exp_f32_e32 v10, v81
	v_exp_f32_e32 v4, v97
	v_exp_f32_e32 v228, v98
	v_add_f32_e32 v11, v226, v227
	v_pk_add_f32 v[12:13], v[10:11], v[4:5]
	s_nop 0
	v_pk_add_f32 v[14:15], v[12:13], v[12:13] op_sel_hi:[0,1]
	v_exp_f32_e32 v11, v82
	v_exp_f32_e32 v12, v83
	v_exp_f32_e32 v14, v99
	v_cvt_pk_bf16_f32 v10, v226, v10
	v_add_f32_e32 v13, v11, v228
	v_cvt_pk_bf16_f32 v11, v11, v12
	v_pk_add_f32 v[80:81], v[12:13], v[14:15]
	v_exp_f32_e32 v13, v84
	v_pk_add_f32 v[96:97], v[80:81], v[80:81] op_sel_hi:[0,1]
	v_exp_f32_e32 v15, v100
	v_exp_f32_e32 v80, v85
	v_exp_f32_e32 v96, v101
	v_cvt_pk_bf16_f32 v12, v13, v80
	v_add_f32_e32 v81, v13, v15
	v_pk_add_f32 v[82:83], v[80:81], v[96:97]
	s_nop 0
	v_pk_add_f32 v[98:99], v[82:83], v[82:83] op_sel_hi:[0,1]
	v_exp_f32_e32 v81, v86
	v_exp_f32_e32 v97, v102
	v_exp_f32_e32 v82, v87
	v_exp_f32_e32 v98, v103
	v_cvt_pk_bf16_f32 v13, v81, v82
	v_add_f32_e32 v83, v81, v97
	v_pk_add_f32 v[84:85], v[82:83], v[98:99]
	s_nop 0
	v_pk_add_f32 v[100:101], v[84:85], v[84:85] op_sel_hi:[0,1]
	v_exp_f32_e32 v83, v88
	v_exp_f32_e32 v99, v104
	v_exp_f32_e32 v84, v89
	v_exp_f32_e32 v100, v105
	v_exp_f32_e32 v104, v95
	v_add_f32_e32 v85, v83, v99
	v_cvt_pk_bf16_f32 v80, v83, v84
	v_pk_add_f32 v[86:87], v[84:85], v[100:101]
	v_exp_f32_e32 v85, v90
	v_pk_add_f32 v[102:103], v[86:87], v[86:87] op_sel_hi:[0,1]
	v_exp_f32_e32 v101, v106
	v_exp_f32_e32 v86, v91
	v_exp_f32_e32 v102, v107
	v_cvt_pk_bf16_f32 v81, v85, v86
	v_add_f32_e32 v87, v85, v101
	v_pk_add_f32 v[88:89], v[86:87], v[102:103]
	s_nop 0
	v_pk_add_f32 v[90:91], v[88:89], v[88:89] op_sel_hi:[0,1]
	v_exp_f32_e32 v87, v92
	v_exp_f32_e32 v103, v108
	v_exp_f32_e32 v88, v93
	v_exp_f32_e32 v90, v109
	v_cvt_pk_bf16_f32 v82, v87, v88
	v_add_f32_e32 v89, v87, v103
	v_pk_add_f32 v[92:93], v[88:89], v[90:91]
	s_nop 0
	v_pk_add_f32 v[92:93], v[92:93], v[92:93] op_sel_hi:[0,1]
	v_exp_f32_e32 v89, v94
	v_exp_f32_e32 v91, v110
	v_exp_f32_e32 v92, v111
	v_cvt_pk_bf16_f32 v83, v89, v104
	v_cvt_pk_bf16_f32 v84, v227, v4
	v_add_f32_e32 v105, v89, v91
	v_pk_add_f32 v[94:95], v[104:105], v[92:93]
	v_add_u32_e32 v4, s5, v223
	v_add_f32_e32 v238, v94, v95
	v_cvt_pk_bf16_f32 v85, v228, v14
	v_cvt_pk_bf16_f32 v86, v15, v96
	v_cvt_pk_bf16_f32 v87, v97, v98
	v_cvt_pk_bf16_f32 v88, v99, v100
	v_cvt_pk_bf16_f32 v89, v101, v102
	v_cvt_pk_bf16_f32 v90, v103, v90
	v_cvt_pk_bf16_f32 v91, v91, v92
	ds_read_b64_tr_b16 v[92:93], v4 offset:18432
	ds_read_b64_tr_b16 v[94:95], v4 offset:20992
	ds_read_b64_tr_b16 v[96:97], v4 offset:18496
	ds_read_b64_tr_b16 v[98:99], v4 offset:21056
	ds_read_b64_tr_b16 v[100:101], v4 offset:18560
	ds_read_b64_tr_b16 v[102:103], v4 offset:21120
	ds_read_b64_tr_b16 v[104:105], v4 offset:18624
	ds_read_b64_tr_b16 v[106:107], v4 offset:21184
	ds_read_b64_tr_b16 v[108:109], v4 offset:23552
	ds_read_b64_tr_b16 v[110:111], v4 offset:26112
	ds_read_b64_tr_b16 v[226:227], v4 offset:23616
	ds_read_b64_tr_b16 v[228:229], v4 offset:26176
	ds_read_b64_tr_b16 v[230:231], v4 offset:23680
	ds_read_b64_tr_b16 v[232:233], v4 offset:26240
	ds_read_b64_tr_b16 v[234:235], v4 offset:23744
	ds_read_b64_tr_b16 v[236:237], v4 offset:26304
	s_waitcnt lgkmcnt(14)
	v_mfma_f32_32x32x16_bf16 v[64:79], v[92:95], v[10:13], v[64:79]
	s_waitcnt lgkmcnt(12)
	v_mfma_f32_32x32x16_bf16 v[48:63], v[96:99], v[10:13], v[48:63]
	s_waitcnt lgkmcnt(10)
	v_mfma_f32_32x32x16_bf16 v[32:47], v[100:103], v[10:13], v[32:47]
	s_waitcnt lgkmcnt(8)
	v_mfma_f32_32x32x16_bf16 v[16:31], v[104:107], v[10:13], v[16:31]
	ds_read_b64_tr_b16 v[10:11], v4 offset:28672
	ds_read_b64_tr_b16 v[92:93], v4 offset:28736
	ds_read_b64_tr_b16 v[96:97], v4 offset:28800
	ds_read_b64_tr_b16 v[100:101], v4 offset:28864
	ds_read_b64_tr_b16 v[12:13], v4 offset:31232
	ds_read_b64_tr_b16 v[94:95], v4 offset:31296
	ds_read_b64_tr_b16 v[98:99], v4 offset:31360
	ds_read_b64_tr_b16 v[102:103], v4 offset:31424
	s_waitcnt lgkmcnt(14)
	v_mfma_f32_32x32x16_bf16 v[64:79], v[108:111], v[80:83], v[64:79]
	s_waitcnt lgkmcnt(12)
	v_mfma_f32_32x32x16_bf16 v[48:63], v[226:229], v[80:83], v[48:63]
	s_waitcnt lgkmcnt(10)
	v_mfma_f32_32x32x16_bf16 v[32:47], v[230:233], v[80:83], v[32:47]
	s_waitcnt lgkmcnt(8)
	v_mfma_f32_32x32x16_bf16 v[16:31], v[234:237], v[80:83], v[16:31]
	ds_read_b64_tr_b16 v[80:81], v4 offset:33792
	ds_read_b64_tr_b16 v[104:105], v4 offset:33856
	ds_read_b64_tr_b16 v[108:109], v4 offset:33920
	ds_read_b64_tr_b16 v[226:227], v4 offset:33984
	ds_read_b64_tr_b16 v[82:83], v4 offset:36352
	ds_read_b64_tr_b16 v[106:107], v4 offset:36416
	ds_read_b64_tr_b16 v[110:111], v4 offset:36480
	ds_read_b64_tr_b16 v[228:229], v4 offset:36544
	s_waitcnt lgkmcnt(11)
	v_mfma_f32_32x32x16_bf16 v[64:79], v[10:13], v[84:87], v[64:79]
	s_waitcnt lgkmcnt(10)
	v_mfma_f32_32x32x16_bf16 v[48:63], v[92:95], v[84:87], v[48:63]
	s_waitcnt lgkmcnt(9)
	v_mfma_f32_32x32x16_bf16 v[32:47], v[96:99], v[84:87], v[32:47]
	s_waitcnt lgkmcnt(8)
	v_mfma_f32_32x32x16_bf16 v[16:31], v[100:103], v[84:87], v[16:31]
	s_waitcnt lgkmcnt(3)
	v_mfma_f32_32x32x16_bf16 v[64:79], v[80:83], v[88:91], v[64:79]
	s_waitcnt lgkmcnt(2)
	v_mfma_f32_32x32x16_bf16 v[48:63], v[104:107], v[88:91], v[48:63]
	s_waitcnt lgkmcnt(1)
	v_mfma_f32_32x32x16_bf16 v[32:47], v[108:111], v[88:91], v[32:47]
	s_waitcnt lgkmcnt(0)
	v_mfma_f32_32x32x16_bf16 v[16:31], v[226:229], v[88:91], v[16:31]
	v_add_f32_e32 v224, v224, v238
	s_cmp_eq_u32 s7, 0
	s_cbranch_scc0 .LBB0_738
	s_branch .LBB0_739

.LBB0_757:
	v_exp_f32_e32 v7, v80
	v_exp_f32_e32 v226, v96
	v_exp_f32_e32 v8, v81
	v_exp_f32_e32 v4, v97
	v_exp_f32_e32 v227, v98
	v_add_f32_e32 v9, v7, v226
	v_exp_f32_e32 v98, v91
	v_pk_add_f32 v[10:11], v[8:9], v[4:5]
	v_exp_f32_e32 v9, v82
	v_pk_add_f32 v[96:97], v[10:11], v[10:11] op_sel_hi:[0,1]
	v_exp_f32_e32 v10, v83
	v_exp_f32_e32 v96, v99
	v_add_f32_e32 v11, v9, v227
	v_cvt_pk_bf16_f32 v8, v7, v8
	v_cvt_pk_bf16_f32 v9, v9, v10
	v_pk_add_f32 v[12:13], v[10:11], v[96:97]
	v_exp_f32_e32 v11, v84
	v_pk_add_f32 v[82:83], v[12:13], v[12:13] op_sel_hi:[0,1]
	v_exp_f32_e32 v97, v100
	v_exp_f32_e32 v12, v85
	v_exp_f32_e32 v82, v101
	v_exp_f32_e32 v100, v93
	v_add_f32_e32 v13, v11, v97
	v_cvt_pk_bf16_f32 v10, v11, v12
	v_pk_add_f32 v[14:15], v[12:13], v[82:83]
	v_exp_f32_e32 v13, v86
	v_pk_add_f32 v[84:85], v[14:15], v[14:15] op_sel_hi:[0,1]
	v_exp_f32_e32 v83, v102
	v_exp_f32_e32 v14, v87
	v_exp_f32_e32 v84, v103
	v_exp_f32_e32 v102, v95
	v_add_f32_e32 v15, v13, v83
	v_cvt_pk_bf16_f32 v11, v13, v14
	v_pk_add_f32 v[80:81], v[14:15], v[84:85]
	v_exp_f32_e32 v15, v88
	v_pk_add_f32 v[86:87], v[80:81], v[80:81] op_sel_hi:[0,1]
	v_exp_f32_e32 v85, v104
	v_exp_f32_e32 v80, v89
	v_exp_f32_e32 v86, v105
	v_cvt_pk_bf16_f32 v12, v15, v80
	v_add_f32_e32 v81, v15, v85
	v_pk_add_f32 v[88:89], v[80:81], v[86:87]
	s_nop 0
	v_pk_add_f32 v[88:89], v[88:89], v[88:89] op_sel_hi:[0,1]
	v_exp_f32_e32 v81, v90
	v_exp_f32_e32 v87, v106
	v_exp_f32_e32 v88, v107
	v_cvt_pk_bf16_f32 v13, v81, v98
	v_add_f32_e32 v99, v81, v87
	v_pk_add_f32 v[90:91], v[98:99], v[88:89]
	v_exp_f32_e32 v89, v92
	v_pk_add_f32 v[90:91], v[90:91], v[90:91] op_sel_hi:[0,1]
	v_exp_f32_e32 v99, v108
	v_exp_f32_e32 v90, v109
	v_cvt_pk_bf16_f32 v14, v89, v100
	v_add_f32_e32 v101, v89, v99
	v_pk_add_f32 v[92:93], v[100:101], v[90:91]
	v_exp_f32_e32 v91, v94
	v_pk_add_f32 v[92:93], v[92:93], v[92:93] op_sel_hi:[0,1]
	v_exp_f32_e32 v101, v110
	v_exp_f32_e32 v92, v111
	v_cvt_pk_bf16_f32 v15, v91, v102
	v_cvt_pk_bf16_f32 v80, v226, v4
	v_add_f32_e32 v103, v91, v101
	v_pk_add_f32 v[94:95], v[102:103], v[92:93]
	v_add_u32_e32 v4, s46, v223
	v_add_f32_e32 v234, v94, v95
	v_cvt_pk_bf16_f32 v81, v227, v96
	v_cvt_pk_bf16_f32 v82, v97, v82
	v_cvt_pk_bf16_f32 v83, v83, v84
	v_cvt_pk_bf16_f32 v84, v85, v86
	v_cvt_pk_bf16_f32 v85, v87, v88
	v_cvt_pk_bf16_f32 v86, v99, v90
	v_cvt_pk_bf16_f32 v87, v101, v92
	ds_read_b64_tr_b16 v[88:89], v4 offset:18432
	ds_read_b64_tr_b16 v[90:91], v4 offset:20992
	ds_read_b64_tr_b16 v[92:93], v4 offset:18496
	ds_read_b64_tr_b16 v[94:95], v4 offset:21056
	ds_read_b64_tr_b16 v[96:97], v4 offset:18560
	ds_read_b64_tr_b16 v[98:99], v4 offset:21120
	ds_read_b64_tr_b16 v[100:101], v4 offset:18624
	ds_read_b64_tr_b16 v[102:103], v4 offset:21184
	ds_read_b64_tr_b16 v[104:105], v4 offset:23552
	ds_read_b64_tr_b16 v[106:107], v4 offset:26112
	ds_read_b64_tr_b16 v[108:109], v4 offset:23616
	ds_read_b64_tr_b16 v[110:111], v4 offset:26176
	ds_read_b64_tr_b16 v[226:227], v4 offset:23680
	ds_read_b64_tr_b16 v[228:229], v4 offset:26240
	ds_read_b64_tr_b16 v[230:231], v4 offset:23744
	ds_read_b64_tr_b16 v[232:233], v4 offset:26304
	s_waitcnt lgkmcnt(14)
	v_mfma_f32_32x32x16_bf16 v[64:79], v[88:91], v[8:11], v[64:79]
	s_waitcnt lgkmcnt(12)
	v_mfma_f32_32x32x16_bf16 v[48:63], v[92:95], v[8:11], v[48:63]
	s_waitcnt lgkmcnt(10)
	v_mfma_f32_32x32x16_bf16 v[32:47], v[96:99], v[8:11], v[32:47]
	s_waitcnt lgkmcnt(8)
	v_mfma_f32_32x32x16_bf16 v[16:31], v[100:103], v[8:11], v[16:31]
	ds_read_b64_tr_b16 v[8:9], v4 offset:28672
	ds_read_b64_tr_b16 v[88:89], v4 offset:28736
	ds_read_b64_tr_b16 v[92:93], v4 offset:28800
	ds_read_b64_tr_b16 v[96:97], v4 offset:28864
	ds_read_b64_tr_b16 v[10:11], v4 offset:31232
	ds_read_b64_tr_b16 v[90:91], v4 offset:31296
	ds_read_b64_tr_b16 v[94:95], v4 offset:31360
	ds_read_b64_tr_b16 v[98:99], v4 offset:31424
	s_waitcnt lgkmcnt(14)
	v_mfma_f32_32x32x16_bf16 v[64:79], v[104:107], v[12:15], v[64:79]
	s_waitcnt lgkmcnt(12)
	v_mfma_f32_32x32x16_bf16 v[48:63], v[108:111], v[12:15], v[48:63]
	s_waitcnt lgkmcnt(10)
	v_mfma_f32_32x32x16_bf16 v[32:47], v[226:229], v[12:15], v[32:47]
	s_waitcnt lgkmcnt(8)
	v_mfma_f32_32x32x16_bf16 v[16:31], v[230:233], v[12:15], v[16:31]
	ds_read_b64_tr_b16 v[12:13], v4 offset:33792
	ds_read_b64_tr_b16 v[100:101], v4 offset:33856
	ds_read_b64_tr_b16 v[104:105], v4 offset:33920
	ds_read_b64_tr_b16 v[108:109], v4 offset:33984
	ds_read_b64_tr_b16 v[14:15], v4 offset:36352
	ds_read_b64_tr_b16 v[102:103], v4 offset:36416
	ds_read_b64_tr_b16 v[106:107], v4 offset:36480
	ds_read_b64_tr_b16 v[110:111], v4 offset:36544
	s_waitcnt lgkmcnt(11)
	v_mfma_f32_32x32x16_bf16 v[64:79], v[8:11], v[80:83], v[64:79]
	s_waitcnt lgkmcnt(10)
	v_mfma_f32_32x32x16_bf16 v[48:63], v[88:91], v[80:83], v[48:63]
	s_waitcnt lgkmcnt(9)
	v_mfma_f32_32x32x16_bf16 v[32:47], v[92:95], v[80:83], v[32:47]
	s_waitcnt lgkmcnt(8)
	v_mfma_f32_32x32x16_bf16 v[16:31], v[96:99], v[80:83], v[16:31]
	s_waitcnt lgkmcnt(3)
	v_mfma_f32_32x32x16_bf16 v[64:79], v[12:15], v[84:87], v[64:79]
	s_waitcnt lgkmcnt(2)
	v_mfma_f32_32x32x16_bf16 v[48:63], v[100:103], v[84:87], v[48:63]
	s_waitcnt lgkmcnt(1)
	v_mfma_f32_32x32x16_bf16 v[32:47], v[104:107], v[84:87], v[32:47]
	s_waitcnt lgkmcnt(0)
	v_mfma_f32_32x32x16_bf16 v[16:31], v[108:111], v[84:87], v[16:31]
	v_add_f32_e32 v224, v224, v234
	s_andn2_b64 vcc, exec, s[16:17]
	s_cbranch_vccnz .LBB0_734

.LBB0_1182:
	v_exp_f32_e32 v100, v160
	v_exp_f32_e32 v101, v2
	v_exp_f32_e32 v4, v161
	v_exp_f32_e32 v80, v3
	v_exp_f32_e32 v102, v6
	v_add_f32_e32 v81, v101, v100
	v_exp_f32_e32 v82, v7
	v_pk_add_f32 v[2:3], v[80:81], v[4:5]
	v_exp_f32_e32 v81, v164
	v_pk_add_f32 v[2:3], v[2:3], v[2:3] op_sel_hi:[0,1]
	v_exp_f32_e32 v2, v165
	v_exp_f32_e32 v84, v11
	v_add_f32_e32 v83, v102, v81
	v_exp_f32_e32 v86, v157
	v_pk_add_f32 v[6:7], v[82:83], v[2:3]
	v_exp_f32_e32 v3, v168
	v_pk_add_f32 v[6:7], v[6:7], v[6:7] op_sel_hi:[0,1]
	v_exp_f32_e32 v83, v10
	v_exp_f32_e32 v6, v169
	v_exp_f32_e32 v90, v15
	v_exp_f32_e32 v92, v13
	v_add_f32_e32 v85, v83, v3
	v_pk_add_f32 v[10:11], v[84:85], v[6:7]
	v_exp_f32_e32 v7, v172
	v_pk_add_f32 v[10:11], v[10:11], v[10:11] op_sel_hi:[0,1]
	v_exp_f32_e32 v85, v156
	v_exp_f32_e32 v10, v173
	v_exp_f32_e32 v94, v9
	v_exp_f32_e32 v98, v1
	v_add_f32_e32 v87, v85, v7
	v_pk_add_f32 v[88:89], v[86:87], v[10:11]
	v_exp_f32_e32 v11, v170
	v_pk_add_f32 v[88:89], v[88:89], v[88:89] op_sel_hi:[0,1]
	v_exp_f32_e32 v87, v14
	v_exp_f32_e32 v88, v171
	v_add_f32_e32 v91, v87, v11
	v_pk_add_f32 v[14:15], v[90:91], v[88:89]
	v_exp_f32_e32 v89, v166
	v_pk_add_f32 v[14:15], v[14:15], v[14:15] op_sel_hi:[0,1]
	v_exp_f32_e32 v91, v12
	v_exp_f32_e32 v14, v167
	v_add_f32_e32 v93, v91, v89
	v_pk_add_f32 v[12:13], v[92:93], v[14:15]
	v_exp_f32_e32 v15, v162
	v_pk_add_f32 v[12:13], v[12:13], v[12:13] op_sel_hi:[0,1]
	v_exp_f32_e32 v93, v8
	v_exp_f32_e32 v12, v163
	v_add_f32_e32 v95, v93, v15
	v_pk_add_f32 v[8:9], v[94:95], v[12:13]
	v_exp_f32_e32 v95, v0
	v_pk_add_f32 v[96:97], v[8:9], v[8:9] op_sel_hi:[0,1]
	v_exp_f32_e32 v9, v158
	v_exp_f32_e32 v96, v159
	v_add_f32_e32 v99, v95, v9
	v_pk_add_f32 v[0:1], v[98:99], v[96:97]
	s_nop 0
	v_add_f32_e32 v160, v0, v1
	v_cvt_pk_bf16_f32 v0, v100, v4
	v_add_u32_e32 v4, s47, v181
	v_cvt_pk_bf16_f32 v1, v81, v2
	v_cvt_pk_bf16_f32 v2, v3, v6
	v_cvt_pk_bf16_f32 v3, v7, v10
	v_cvt_pk_bf16_f32 v6, v11, v88
	v_cvt_pk_bf16_f32 v7, v89, v14
	v_cvt_pk_bf16_f32 v8, v15, v12
	v_cvt_pk_bf16_f32 v9, v9, v96
	v_cvt_pk_bf16_f32 v10, v101, v80
	v_cvt_pk_bf16_f32 v11, v102, v82
	v_cvt_pk_bf16_f32 v12, v83, v84
	v_cvt_pk_bf16_f32 v13, v85, v86
	v_cvt_pk_bf16_f32 v80, v87, v90
	v_cvt_pk_bf16_f32 v81, v91, v92
	v_cvt_pk_bf16_f32 v82, v93, v94
	v_cvt_pk_bf16_f32 v83, v95, v98
	ds_read_b64_tr_b16 v[84:85], v4 offset:34816
	ds_read_b64_tr_b16 v[86:87], v4 offset:37376
	ds_read_b64_tr_b16 v[88:89], v4 offset:34880
	ds_read_b64_tr_b16 v[90:91], v4 offset:37440
	ds_read_b64_tr_b16 v[92:93], v4 offset:34944
	ds_read_b64_tr_b16 v[94:95], v4 offset:37504
	ds_read_b64_tr_b16 v[96:97], v4 offset:35008
	ds_read_b64_tr_b16 v[98:99], v4 offset:37568
	ds_read_b64_tr_b16 v[100:101], v4 offset:39936
	ds_read_b64_tr_b16 v[102:103], v4 offset:42496
	ds_read_b64_tr_b16 v[104:105], v4 offset:40000
	ds_read_b64_tr_b16 v[106:107], v4 offset:42560
	ds_read_b64_tr_b16 v[108:109], v4 offset:40064
	ds_read_b64_tr_b16 v[110:111], v4 offset:42624
	ds_read_b64_tr_b16 v[156:157], v4 offset:40128
	ds_read_b64_tr_b16 v[158:159], v4 offset:42688
	s_waitcnt lgkmcnt(14)
	v_mfma_f32_32x32x16_bf16 v[64:79], v[84:87], v[0:3], v[64:79]
	s_waitcnt lgkmcnt(12)
	v_mfma_f32_32x32x16_bf16 v[48:63], v[88:91], v[0:3], v[48:63]
	s_waitcnt lgkmcnt(10)
	v_mfma_f32_32x32x16_bf16 v[32:47], v[92:95], v[0:3], v[32:47]
	s_waitcnt lgkmcnt(8)
	v_mfma_f32_32x32x16_bf16 v[16:31], v[96:99], v[0:3], v[16:31]
	ds_read_b64_tr_b16 v[0:1], v4 offset:45056
	ds_read_b64_tr_b16 v[84:85], v4 offset:45120
	ds_read_b64_tr_b16 v[88:89], v4 offset:45184
	ds_read_b64_tr_b16 v[92:93], v4 offset:45248
	ds_read_b64_tr_b16 v[2:3], v4 offset:47616
	ds_read_b64_tr_b16 v[86:87], v4 offset:47680
	ds_read_b64_tr_b16 v[90:91], v4 offset:47744
	ds_read_b64_tr_b16 v[94:95], v4 offset:47808
	s_waitcnt lgkmcnt(14)
	v_mfma_f32_32x32x16_bf16 v[64:79], v[100:103], v[6:9], v[64:79]
	s_waitcnt lgkmcnt(12)
	v_mfma_f32_32x32x16_bf16 v[48:63], v[104:107], v[6:9], v[48:63]
	s_waitcnt lgkmcnt(10)
	v_mfma_f32_32x32x16_bf16 v[32:47], v[108:111], v[6:9], v[32:47]
	s_waitcnt lgkmcnt(8)
	v_mfma_f32_32x32x16_bf16 v[16:31], v[156:159], v[6:9], v[16:31]
	ds_read_b64_tr_b16 v[6:7], v4 offset:50176
	ds_read_b64_tr_b16 v[96:97], v4 offset:50240
	ds_read_b64_tr_b16 v[100:101], v4 offset:50304
	ds_read_b64_tr_b16 v[104:105], v4 offset:50368
	ds_read_b64_tr_b16 v[8:9], v4 offset:52736
	ds_read_b64_tr_b16 v[98:99], v4 offset:52800
	ds_read_b64_tr_b16 v[102:103], v4 offset:52864
	ds_read_b64_tr_b16 v[106:107], v4 offset:52928
	s_waitcnt lgkmcnt(11)
	v_mfma_f32_32x32x16_bf16 v[64:79], v[0:3], v[10:13], v[64:79]
	s_waitcnt lgkmcnt(10)
	v_mfma_f32_32x32x16_bf16 v[48:63], v[84:87], v[10:13], v[48:63]
	s_waitcnt lgkmcnt(9)
	v_mfma_f32_32x32x16_bf16 v[32:47], v[88:91], v[10:13], v[32:47]
	s_waitcnt lgkmcnt(8)
	v_mfma_f32_32x32x16_bf16 v[16:31], v[92:95], v[10:13], v[16:31]
	s_waitcnt lgkmcnt(3)
	v_mfma_f32_32x32x16_bf16 v[64:79], v[6:9], v[80:83], v[64:79]
	s_waitcnt lgkmcnt(2)
	v_mfma_f32_32x32x16_bf16 v[48:63], v[96:99], v[80:83], v[48:63]
	s_waitcnt lgkmcnt(1)
	v_mfma_f32_32x32x16_bf16 v[32:47], v[100:103], v[80:83], v[32:47]
	s_waitcnt lgkmcnt(0)
	v_mfma_f32_32x32x16_bf16 v[16:31], v[104:107], v[80:83], v[16:31]
	v_add_f32_e32 v205, v205, v160
	s_cmp_eq_u32 s92, 0
	s_cbranch_scc0 .LBB0_766
	s_branch .LBB0_767

.LBB0_1193:
	v_exp_f32_e32 v100, v160
	v_exp_f32_e32 v101, v2
	v_exp_f32_e32 v80, v161
	v_exp_f32_e32 v4, v3
	v_exp_f32_e32 v102, v6
	v_add_f32_e32 v81, v100, v101
	v_exp_f32_e32 v90, v171
	v_pk_add_f32 v[2:3], v[80:81], v[4:5]
	v_exp_f32_e32 v81, v164
	v_pk_add_f32 v[82:83], v[2:3], v[2:3] op_sel_hi:[0,1]
	v_exp_f32_e32 v2, v165
	v_exp_f32_e32 v82, v7
	v_add_f32_e32 v3, v81, v102
	v_exp_f32_e32 v92, v167
	v_exp_f32_e32 v98, v159
	v_pk_add_f32 v[6:7], v[2:3], v[82:83]
	v_exp_f32_e32 v3, v168
	v_pk_add_f32 v[84:85], v[6:7], v[6:7] op_sel_hi:[0,1]
	v_exp_f32_e32 v83, v10
	v_exp_f32_e32 v6, v169
	v_exp_f32_e32 v84, v11
	v_add_f32_e32 v7, v3, v83
	v_pk_add_f32 v[10:11], v[6:7], v[84:85]
	s_nop 0
	v_pk_add_f32 v[86:87], v[10:11], v[10:11] op_sel_hi:[0,1]
	v_exp_f32_e32 v7, v172
	v_exp_f32_e32 v85, v156
	v_exp_f32_e32 v10, v173
	v_exp_f32_e32 v86, v157
	v_add_f32_e32 v11, v7, v85
	v_pk_add_f32 v[88:89], v[10:11], v[86:87]
	s_nop 0
	v_pk_add_f32 v[88:89], v[88:89], v[88:89] op_sel_hi:[0,1]
	v_exp_f32_e32 v11, v170
	v_exp_f32_e32 v87, v14
	v_exp_f32_e32 v88, v15
	v_add_f32_e32 v91, v11, v87
	v_pk_add_f32 v[14:15], v[90:91], v[88:89]
	v_exp_f32_e32 v89, v166
	v_pk_add_f32 v[14:15], v[14:15], v[14:15] op_sel_hi:[0,1]
	v_exp_f32_e32 v91, v12
	v_exp_f32_e32 v14, v13
	v_add_f32_e32 v93, v89, v91
	v_pk_add_f32 v[12:13], v[92:93], v[14:15]
	v_exp_f32_e32 v15, v162
	v_pk_add_f32 v[94:95], v[12:13], v[12:13] op_sel_hi:[0,1]
	v_exp_f32_e32 v93, v8
	v_exp_f32_e32 v12, v163
	v_exp_f32_e32 v94, v9
	v_add_f32_e32 v13, v15, v93
	v_pk_add_f32 v[8:9], v[12:13], v[94:95]
	s_nop 0
	v_pk_add_f32 v[96:97], v[8:9], v[8:9] op_sel_hi:[0,1]
	v_exp_f32_e32 v9, v158
	v_exp_f32_e32 v95, v0
	v_exp_f32_e32 v96, v1
	v_add_f32_e32 v99, v9, v95
	v_pk_add_f32 v[0:1], v[98:99], v[96:97]
	s_nop 0
	v_add_f32_e32 v160, v0, v1
	v_cvt_pk_bf16_f32 v0, v100, v80
	v_cvt_pk_bf16_f32 v1, v81, v2
	v_cvt_pk_bf16_f32 v2, v3, v6
	v_cvt_pk_bf16_f32 v3, v7, v10
	v_cvt_pk_bf16_f32 v6, v11, v90
	v_cvt_pk_bf16_f32 v7, v89, v92
	v_cvt_pk_bf16_f32 v8, v15, v12
	v_cvt_pk_bf16_f32 v9, v9, v98
	v_cvt_pk_bf16_f32 v10, v101, v4
	v_add_u32_e32 v4, s45, v181
	v_cvt_pk_bf16_f32 v11, v102, v82
	v_cvt_pk_bf16_f32 v12, v83, v84
	v_cvt_pk_bf16_f32 v13, v85, v86
	v_cvt_pk_bf16_f32 v80, v87, v88
	v_cvt_pk_bf16_f32 v81, v91, v14
	v_cvt_pk_bf16_f32 v82, v93, v94
	v_cvt_pk_bf16_f32 v83, v95, v96
	ds_read_b64_tr_b16 v[84:85], v4 offset:34816
	ds_read_b64_tr_b16 v[86:87], v4 offset:37376
	ds_read_b64_tr_b16 v[88:89], v4 offset:34880
	ds_read_b64_tr_b16 v[90:91], v4 offset:37440
	ds_read_b64_tr_b16 v[92:93], v4 offset:34944
	ds_read_b64_tr_b16 v[94:95], v4 offset:37504
	ds_read_b64_tr_b16 v[96:97], v4 offset:35008
	ds_read_b64_tr_b16 v[98:99], v4 offset:37568
	ds_read_b64_tr_b16 v[100:101], v4 offset:39936
	ds_read_b64_tr_b16 v[102:103], v4 offset:42496
	ds_read_b64_tr_b16 v[104:105], v4 offset:40000
	ds_read_b64_tr_b16 v[106:107], v4 offset:42560
	ds_read_b64_tr_b16 v[108:109], v4 offset:40064
	ds_read_b64_tr_b16 v[110:111], v4 offset:42624
	ds_read_b64_tr_b16 v[156:157], v4 offset:40128
	ds_read_b64_tr_b16 v[158:159], v4 offset:42688
	s_waitcnt lgkmcnt(14)
	v_mfma_f32_32x32x16_bf16 v[64:79], v[84:87], v[0:3], v[64:79]
	s_waitcnt lgkmcnt(12)
	v_mfma_f32_32x32x16_bf16 v[48:63], v[88:91], v[0:3], v[48:63]
	s_waitcnt lgkmcnt(10)
	v_mfma_f32_32x32x16_bf16 v[32:47], v[92:95], v[0:3], v[32:47]
	s_waitcnt lgkmcnt(8)
	v_mfma_f32_32x32x16_bf16 v[16:31], v[96:99], v[0:3], v[16:31]
	ds_read_b64_tr_b16 v[0:1], v4 offset:45056
	ds_read_b64_tr_b16 v[84:85], v4 offset:45120
	ds_read_b64_tr_b16 v[88:89], v4 offset:45184
	ds_read_b64_tr_b16 v[92:93], v4 offset:45248
	ds_read_b64_tr_b16 v[2:3], v4 offset:47616
	ds_read_b64_tr_b16 v[86:87], v4 offset:47680
	ds_read_b64_tr_b16 v[90:91], v4 offset:47744
	ds_read_b64_tr_b16 v[94:95], v4 offset:47808
	s_waitcnt lgkmcnt(14)
	v_mfma_f32_32x32x16_bf16 v[64:79], v[100:103], v[6:9], v[64:79]
	s_waitcnt lgkmcnt(12)
	v_mfma_f32_32x32x16_bf16 v[48:63], v[104:107], v[6:9], v[48:63]
	s_waitcnt lgkmcnt(10)
	v_mfma_f32_32x32x16_bf16 v[32:47], v[108:111], v[6:9], v[32:47]
	s_waitcnt lgkmcnt(8)
	v_mfma_f32_32x32x16_bf16 v[16:31], v[156:159], v[6:9], v[16:31]
	ds_read_b64_tr_b16 v[6:7], v4 offset:50176
	ds_read_b64_tr_b16 v[96:97], v4 offset:50240
	ds_read_b64_tr_b16 v[100:101], v4 offset:50304
	ds_read_b64_tr_b16 v[104:105], v4 offset:50368
	ds_read_b64_tr_b16 v[8:9], v4 offset:52736
	ds_read_b64_tr_b16 v[98:99], v4 offset:52800
	ds_read_b64_tr_b16 v[102:103], v4 offset:52864
	ds_read_b64_tr_b16 v[106:107], v4 offset:52928
	s_waitcnt lgkmcnt(11)
	v_mfma_f32_32x32x16_bf16 v[64:79], v[0:3], v[10:13], v[64:79]
	s_waitcnt lgkmcnt(10)
	v_mfma_f32_32x32x16_bf16 v[48:63], v[84:87], v[10:13], v[48:63]
	s_waitcnt lgkmcnt(9)
	v_mfma_f32_32x32x16_bf16 v[32:47], v[88:91], v[10:13], v[32:47]
	s_waitcnt lgkmcnt(8)
	v_mfma_f32_32x32x16_bf16 v[16:31], v[92:95], v[10:13], v[16:31]
	s_waitcnt lgkmcnt(3)
	v_mfma_f32_32x32x16_bf16 v[64:79], v[6:9], v[80:83], v[64:79]
	s_waitcnt lgkmcnt(2)
	v_mfma_f32_32x32x16_bf16 v[48:63], v[96:99], v[80:83], v[48:63]
	s_waitcnt lgkmcnt(1)
	v_mfma_f32_32x32x16_bf16 v[32:47], v[100:103], v[80:83], v[32:47]
	s_waitcnt lgkmcnt(0)
	v_mfma_f32_32x32x16_bf16 v[16:31], v[104:107], v[80:83], v[16:31]
	v_add_f32_e32 v205, v205, v160
	s_andn2_b64 vcc, exec, s[14:15]
	s_cbranch_vccnz .LBB0_762

; __global__ void __launch_bounds__(512, 2) mega(Args a) {
;     ...
;                 for (;;) {
;                     if (tid == 0) *s_unit = (int)atomicAdd(ctr, 1u);
;                     __syncthreads();
;                     const int u = *s_unit;
;                     __syncthreads();
;                     if (u >= nunits) break;
.LBB0_1231:
	s_setprio 0
	v_readlane_b32 s28, v251, 4
	v_readlane_b32 s22, v251, 8
	s_mov_b64 s[16:17], 0
	v_readlane_b32 s15, v251, 3
	v_readlane_b32 s29, v251, 5
	v_readlane_b32 s23, v251, 9
